# v21 + duplicate post-barrier lgkmcnt(0) removed in K-loops
# baseline (speedup 1.0000x reference)
.LBB0_303:
	s_ashr_i32 s35, s34, 31
	s_lshl_b64 s[8:9], s[34:35], 20
	s_add_u32 s36, s53, s8
	s_addc_u32 s37, s54, s9
	s_and_b64 s[8:9], s[2:3], exec
	s_cselect_b32 s35, s37, s5
	s_cselect_b32 s52, s36, s4
	s_ashr_i32 s31, s30, 31
	s_lshl_b64 s[8:9], s[30:31], 20
	s_add_u32 s38, s55, s8
	s_addc_u32 s39, s56, s9
	s_and_b64 s[8:9], s[2:3], exec
	s_cselect_b32 s31, s39, s7
	s_cselect_b32 s77, s38, s6
	s_add_u32 s4, s4, 0x80080
	s_addc_u32 s5, s5, 0
	s_add_u32 s78, s6, 0x100
	s_addc_u32 s79, s7, 0
	s_mov_b32 s80, -2
	s_waitcnt lgkmcnt(0)
	ds_read_b128 v[2:5], v234
	ds_read_b128 v[6:9], v234 offset:1024
	ds_read_b128 v[10:13], v234 offset:2048
	ds_read_b128 v[14:17], v234 offset:3072
	ds_read_b128 v[18:21], v235
	ds_read_b128 v[22:25], v235 offset:1024
	ds_read_b128 v[26:29], v235 offset:2048
	ds_read_b128 v[30:33], v235 offset:3072
	s_add_u32 s6, s4, 0xfff80080
	s_addc_u32 s7, s5, -1
	s_cmp_eq_u32 s80, 28
	s_cselect_b32 s9, s35, s7
	s_cselect_b32 s8, s52, s6
	s_cselect_b32 s7, s31, s79
	s_cselect_b32 s6, s77, s78
	v_lshl_add_u64 v[214:215], s[4:5], 0, v[206:207]
	s_add_i32 m0, s43, 0xc000
	ds_read_b128 v[98:101], v236
	ds_read_b128 v[102:105], v236 offset:1024
	ds_read_b128 v[106:109], v236 offset:2048
	ds_read_b128 v[110:113], v236 offset:3072
	ds_read_b128 v[178:181], v236 offset:4096
	ds_read_b128 v[182:185], v236 offset:5120
	ds_read_b128 v[186:189], v236 offset:6144
	ds_read_b128 v[190:193], v236 offset:7168
	global_load_lds_dwordx4 v[214:215], off
	v_lshl_add_u64 v[214:215], s[4:5], 0, v[208:209]
	s_add_i32 m0, s43, 0xe000
	s_nop 0
	global_load_lds_dwordx4 v[214:215], off
	s_waitcnt vmcnt(8)
	s_waitcnt lgkmcnt(0)
	s_barrier
	v_mfma_i32_16x16x64_i8 v[174:177], v[2:5], v[98:101], 0
	v_mfma_i32_16x16x64_i8 v[170:173], v[10:13], v[98:101], 0
	v_mfma_i32_16x16x64_i8 v[158:161], v[2:5], v[106:109], 0
	v_mfma_i32_16x16x64_i8 v[154:157], v[10:13], v[106:109], 0
	v_mfma_i32_16x16x64_i8 v[142:145], v[2:5], v[178:181], 0
	v_mfma_i32_16x16x64_i8 v[138:141], v[10:13], v[178:181], 0
	v_mfma_i32_16x16x64_i8 v[126:129], v[2:5], v[186:189], 0
	v_mfma_i32_16x16x64_i8 v[122:125], v[10:13], v[186:189], 0
	v_mfma_i32_16x16x64_i8 v[174:177], v[6:9], v[102:105], v[174:177]
	v_mfma_i32_16x16x64_i8 v[170:173], v[14:17], v[102:105], v[170:173]
	v_mfma_i32_16x16x64_i8 v[158:161], v[6:9], v[110:113], v[158:161]
	v_mfma_i32_16x16x64_i8 v[154:157], v[14:17], v[110:113], v[154:157]
	v_mfma_i32_16x16x64_i8 v[142:145], v[6:9], v[182:185], v[142:145]
	v_mfma_i32_16x16x64_i8 v[138:141], v[14:17], v[182:185], v[138:141]
	v_mfma_i32_16x16x64_i8 v[126:129], v[6:9], v[190:193], v[126:129]
	v_mfma_i32_16x16x64_i8 v[122:125], v[14:17], v[190:193], v[122:125]
	v_mfma_i32_16x16x64_i8 v[166:169], v[18:21], v[98:101], 0
	v_mfma_i32_16x16x64_i8 v[98:101], v[26:29], v[98:101], 0
	v_mfma_i32_16x16x64_i8 v[166:169], v[22:25], v[102:105], v[166:169]
	v_mfma_i32_16x16x64_i8 v[98:101], v[30:33], v[102:105], v[98:101]
	v_mfma_i32_16x16x64_i8 v[102:105], v[18:21], v[106:109], 0
	v_mfma_i32_16x16x64_i8 v[106:109], v[26:29], v[106:109], 0
	v_mfma_i32_16x16x64_i8 v[130:133], v[26:29], v[178:181], 0
	v_mfma_i32_16x16x64_i8 v[118:121], v[18:21], v[186:189], 0
	v_mfma_i32_16x16x64_i8 v[114:117], v[26:29], v[186:189], 0
	v_mfma_i32_16x16x64_i8 v[102:105], v[22:25], v[110:113], v[102:105]
	v_mfma_i32_16x16x64_i8 v[106:109], v[30:33], v[110:113], v[106:109]
	v_mfma_i32_16x16x64_i8 v[110:113], v[18:21], v[178:181], 0
	v_mfma_i32_16x16x64_i8 v[130:133], v[30:33], v[182:185], v[130:133]
	v_mfma_i32_16x16x64_i8 v[118:121], v[22:25], v[190:193], v[118:121]
	v_mfma_i32_16x16x64_i8 v[114:117], v[30:33], v[190:193], v[114:117]
	v_mfma_i32_16x16x64_i8 v[110:113], v[22:25], v[182:185], v[110:113]
	s_barrier
	s_add_i32 s81, s70, s41
	v_lshl_add_u64 v[226:227], s[6:7], 0, v[196:197]
	s_mov_b32 m0, s81
	ds_read_b128 v[134:137], v236 offset:16384
	ds_read_b128 v[146:149], v236 offset:17408
	ds_read_b128 v[150:153], v236 offset:18432
	ds_read_b128 v[162:165], v236 offset:19456
	ds_read_b128 v[178:181], v236 offset:20480
	ds_read_b128 v[182:185], v236 offset:21504
	ds_read_b128 v[186:189], v236 offset:22528
	ds_read_b128 v[190:193], v236 offset:23552
	global_load_lds_dwordx4 v[226:227], off
	s_add_i32 m0, s81, 0x2000
	s_add_u32 s82, s6, 0x80000
	v_lshl_add_u64 v[244:245], s[6:7], 0, v[198:199]
	s_addc_u32 s83, s7, 0
	s_add_i32 s81, s71, s41
	global_load_lds_dwordx4 v[244:245], off
	v_lshl_add_u64 v[214:215], s[82:83], 0, v[196:197]
	s_mov_b32 m0, s81
	v_lshl_add_u64 v[246:247], s[8:9], 0, v[196:197]
	global_load_lds_dwordx4 v[214:215], off
	v_lshl_add_u64 v[214:215], s[82:83], 0, v[198:199]
	s_add_i32 m0, s81, 0x2000
	v_lshl_add_u64 v[248:249], s[8:9], 0, v[198:199]
	global_load_lds_dwordx4 v[214:215], off
	s_mov_b32 m0, s43
	s_nop 0
	global_load_lds_dwordx4 v[246:247], off
	s_mov_b32 m0, s57
	s_nop 0
	global_load_lds_dwordx4 v[248:249], off
	s_waitcnt vmcnt(8)
	s_waitcnt lgkmcnt(0)
	s_barrier
	v_mfma_i32_16x16x64_i8 v[94:97], v[2:5], v[134:137], 0
	v_mfma_i32_16x16x64_i8 v[90:93], v[10:13], v[134:137], 0
	v_mfma_i32_16x16x64_i8 v[78:81], v[2:5], v[150:153], 0
	v_mfma_i32_16x16x64_i8 v[74:77], v[10:13], v[150:153], 0
	v_mfma_i32_16x16x64_i8 v[62:65], v[2:5], v[178:181], 0
	v_mfma_i32_16x16x64_i8 v[58:61], v[10:13], v[178:181], 0
	v_mfma_i32_16x16x64_i8 v[2:5], v[2:5], v[186:189], 0
	v_mfma_i32_16x16x64_i8 v[94:97], v[6:9], v[146:149], v[94:97]
	v_mfma_i32_16x16x64_i8 v[90:93], v[14:17], v[146:149], v[90:93]
	v_mfma_i32_16x16x64_i8 v[78:81], v[6:9], v[162:165], v[78:81]
	v_mfma_i32_16x16x64_i8 v[74:77], v[14:17], v[162:165], v[74:77]
	v_mfma_i32_16x16x64_i8 v[62:65], v[6:9], v[182:185], v[62:65]
	v_mfma_i32_16x16x64_i8 v[58:61], v[14:17], v[182:185], v[58:61]
	v_mfma_i32_16x16x64_i8 v[2:5], v[6:9], v[190:193], v[2:5]
	v_mfma_i32_16x16x64_i8 v[6:9], v[10:13], v[186:189], 0
	v_mfma_i32_16x16x64_i8 v[6:9], v[14:17], v[190:193], v[6:9]
	v_mfma_i32_16x16x64_i8 v[42:45], v[18:21], v[150:153], 0
	v_mfma_i32_16x16x64_i8 v[70:73], v[22:25], v[162:165], v[42:45]
	v_mfma_i32_16x16x64_i8 v[42:45], v[26:29], v[150:153], 0
	v_mfma_i32_16x16x64_i8 v[66:69], v[30:33], v[162:165], v[42:45]
	v_mfma_i32_16x16x64_i8 v[42:45], v[18:21], v[178:181], 0
	v_mfma_i32_16x16x64_i8 v[10:13], v[18:21], v[134:137], 0
	v_mfma_i32_16x16x64_i8 v[54:57], v[22:25], v[182:185], v[42:45]
	v_mfma_i32_16x16x64_i8 v[42:45], v[26:29], v[178:181], 0
	v_mfma_i32_16x16x64_i8 v[18:21], v[18:21], v[186:189], 0
	v_mfma_i32_16x16x64_i8 v[10:13], v[22:25], v[146:149], v[10:13]
	v_mfma_i32_16x16x64_i8 v[14:17], v[26:29], v[134:137], 0
	v_mfma_i32_16x16x64_i8 v[50:53], v[30:33], v[182:185], v[42:45]
	v_mfma_i32_16x16x64_i8 v[18:21], v[22:25], v[190:193], v[18:21]
	v_mfma_i32_16x16x64_i8 v[22:25], v[26:29], v[186:189], 0
	v_mfma_i32_16x16x64_i8 v[14:17], v[30:33], v[146:149], v[14:17]
	v_mfma_i32_16x16x64_i8 v[22:25], v[30:33], v[190:193], v[22:25]
	s_barrier
	s_add_i32 s81, 0, 0x18000
	s_add_i32 s82, 0, 0x1c000
	v_add_u32_e32 v38, s81, v229
	v_add_u32_e32 v42, s82, v229
	ds_read_b128 v[26:29], v38
	ds_read_b128 v[30:33], v38 offset:1024
	ds_read_b128 v[34:37], v38 offset:2048
	ds_read_b128 v[38:41], v38 offset:3072
	ds_read_b128 v[178:181], v42
	ds_read_b128 v[182:185], v42 offset:1024
	ds_read_b128 v[186:189], v42 offset:2048
	ds_read_b128 v[190:193], v42 offset:3072
	s_add_u32 s8, s8, 0x80000
	s_addc_u32 s9, s9, 0
	s_mov_b32 m0, s60
	v_lshl_add_u64 v[134:135], s[8:9], 0, v[196:197]
	ds_read_b128 v[42:45], v236 offset:32768
	ds_read_b128 v[46:49], v236 offset:33792
	ds_read_b128 v[82:85], v236 offset:34816
	ds_read_b128 v[86:89], v236 offset:35840
	ds_read_b128 v[214:217], v236 offset:36864
	ds_read_b128 v[218:221], v236 offset:37888
	ds_read_b128 v[222:225], v236 offset:38912
	ds_read_b128 v[240:243], v236 offset:39936
	global_load_lds_dwordx4 v[134:135], off
	v_lshl_add_u64 v[134:135], s[8:9], 0, v[198:199]
	s_mov_b32 m0, s61
	s_nop 0
	global_load_lds_dwordx4 v[134:135], off
	s_waitcnt vmcnt(8)
	s_waitcnt lgkmcnt(0)
	s_barrier
	v_mfma_i32_16x16x64_i8 v[134:137], v[26:29], v[42:45], v[174:177]
	v_mfma_i32_16x16x64_i8 v[174:177], v[30:33], v[46:49], v[134:137]
	v_mfma_i32_16x16x64_i8 v[134:137], v[34:37], v[42:45], v[170:173]
	v_mfma_i32_16x16x64_i8 v[170:173], v[38:41], v[46:49], v[134:137]
	v_mfma_i32_16x16x64_i8 v[134:137], v[26:29], v[82:85], v[158:161]
	v_mfma_i32_16x16x64_i8 v[158:161], v[30:33], v[86:89], v[134:137]
	v_mfma_i32_16x16x64_i8 v[134:137], v[34:37], v[82:85], v[154:157]
	v_mfma_i32_16x16x64_i8 v[154:157], v[38:41], v[86:89], v[134:137]
	v_mfma_i32_16x16x64_i8 v[134:137], v[26:29], v[214:217], v[142:145]
	v_mfma_i32_16x16x64_i8 v[142:145], v[30:33], v[218:221], v[134:137]
	v_mfma_i32_16x16x64_i8 v[134:137], v[34:37], v[214:217], v[138:141]
	v_mfma_i32_16x16x64_i8 v[126:129], v[26:29], v[222:225], v[126:129]
	v_mfma_i32_16x16x64_i8 v[122:125], v[34:37], v[222:225], v[122:125]
	v_mfma_i32_16x16x64_i8 v[138:141], v[38:41], v[218:221], v[134:137]
	v_mfma_i32_16x16x64_i8 v[126:129], v[30:33], v[240:243], v[126:129]
	v_mfma_i32_16x16x64_i8 v[122:125], v[38:41], v[240:243], v[122:125]
	v_mfma_i32_16x16x64_i8 v[134:137], v[178:181], v[42:45], v[166:169]
	v_mfma_i32_16x16x64_i8 v[42:45], v[186:189], v[42:45], v[98:101]
	v_mfma_i32_16x16x64_i8 v[162:165], v[190:193], v[46:49], v[42:45]
	v_mfma_i32_16x16x64_i8 v[42:45], v[178:181], v[82:85], v[102:105]
	v_mfma_i32_16x16x64_i8 v[150:153], v[182:185], v[86:89], v[42:45]
	v_mfma_i32_16x16x64_i8 v[42:45], v[186:189], v[82:85], v[106:109]
	v_mfma_i32_16x16x64_i8 v[146:149], v[190:193], v[86:89], v[42:45]
	v_mfma_i32_16x16x64_i8 v[42:45], v[178:181], v[214:217], v[110:113]
	v_mfma_i32_16x16x64_i8 v[166:169], v[182:185], v[46:49], v[134:137]
	v_mfma_i32_16x16x64_i8 v[134:137], v[182:185], v[218:221], v[42:45]
	v_mfma_i32_16x16x64_i8 v[42:45], v[186:189], v[214:217], v[130:133]
	v_mfma_i32_16x16x64_i8 v[130:133], v[190:193], v[218:221], v[42:45]
	v_mfma_i32_16x16x64_i8 v[42:45], v[178:181], v[222:225], v[118:121]
	v_mfma_i32_16x16x64_i8 v[118:121], v[182:185], v[240:243], v[42:45]
	v_mfma_i32_16x16x64_i8 v[42:45], v[186:189], v[222:225], v[114:117]
	v_mfma_i32_16x16x64_i8 v[114:117], v[190:193], v[240:243], v[42:45]
	s_barrier
	s_add_i32 s8, s81, s41
	s_nop 3
	v_lshl_add_u64 v[42:43], v[226:227], 0, s[24:25]
	s_mov_b32 m0, s8
	ds_read_b128 v[82:85], v236 offset:49152
	ds_read_b128 v[98:101], v236 offset:50176
	ds_read_b128 v[102:105], v236 offset:51200
	ds_read_b128 v[106:109], v236 offset:52224
	ds_read_b128 v[110:113], v236 offset:53248
	ds_read_b128 v[214:217], v236 offset:54272
	ds_read_b128 v[218:221], v236 offset:55296
	ds_read_b128 v[222:225], v236 offset:56320
	global_load_lds_dwordx4 v[42:43], off
	s_add_i32 m0, s8, 0x2000
	s_add_u32 s6, s6, 0x80080
	v_lshl_add_u64 v[42:43], v[244:245], 0, s[24:25]
	s_addc_u32 s7, s7, 0
	s_add_i32 s8, s82, s41
	global_load_lds_dwordx4 v[42:43], off
	v_lshl_add_u64 v[42:43], s[6:7], 0, v[196:197]
	s_mov_b32 m0, s8
	s_nop 0
	global_load_lds_dwordx4 v[42:43], off
	v_lshl_add_u64 v[42:43], s[6:7], 0, v[198:199]
	s_add_i32 m0, s8, 0x2000
	s_nop 0
	global_load_lds_dwordx4 v[42:43], off
	v_lshl_add_u64 v[42:43], v[246:247], 0, s[24:25]
	s_mov_b32 m0, s63
	s_nop 0
	global_load_lds_dwordx4 v[42:43], off
	v_lshl_add_u64 v[42:43], v[248:249], 0, s[24:25]
	s_mov_b32 m0, s64
	s_nop 0
	global_load_lds_dwordx4 v[42:43], off
	s_waitcnt vmcnt(8)
	s_waitcnt lgkmcnt(0)
	s_barrier
	v_mfma_i32_16x16x64_i8 v[42:45], v[26:29], v[82:85], v[94:97]
	v_mfma_i32_16x16x64_i8 v[94:97], v[30:33], v[98:101], v[42:45]
	v_mfma_i32_16x16x64_i8 v[42:45], v[34:37], v[82:85], v[90:93]
	v_mfma_i32_16x16x64_i8 v[90:93], v[38:41], v[98:101], v[42:45]
	v_mfma_i32_16x16x64_i8 v[42:45], v[26:29], v[102:105], v[78:81]
	v_mfma_i32_16x16x64_i8 v[78:81], v[30:33], v[106:109], v[42:45]
	v_mfma_i32_16x16x64_i8 v[42:45], v[34:37], v[102:105], v[74:77]
	v_mfma_i32_16x16x64_i8 v[74:77], v[38:41], v[106:109], v[42:45]
	v_mfma_i32_16x16x64_i8 v[42:45], v[26:29], v[110:113], v[62:65]
	v_mfma_i32_16x16x64_i8 v[2:5], v[26:29], v[218:221], v[2:5]
	v_mfma_i32_16x16x64_i8 v[62:65], v[30:33], v[214:217], v[42:45]
	v_mfma_i32_16x16x64_i8 v[42:45], v[34:37], v[110:113], v[58:61]
	v_mfma_i32_16x16x64_i8 v[46:49], v[30:33], v[222:225], v[2:5]
	v_mfma_i32_16x16x64_i8 v[2:5], v[34:37], v[218:221], v[6:9]
	v_mfma_i32_16x16x64_i8 v[58:61], v[38:41], v[214:217], v[42:45]
	v_mfma_i32_16x16x64_i8 v[42:45], v[38:41], v[222:225], v[2:5]
	v_mfma_i32_16x16x64_i8 v[2:5], v[178:181], v[82:85], v[10:13]
	v_mfma_i32_16x16x64_i8 v[86:89], v[182:185], v[98:101], v[2:5]
	v_mfma_i32_16x16x64_i8 v[2:5], v[186:189], v[82:85], v[14:17]
	v_mfma_i32_16x16x64_i8 v[82:85], v[190:193], v[98:101], v[2:5]
	v_mfma_i32_16x16x64_i8 v[2:5], v[178:181], v[102:105], v[70:73]
	v_mfma_i32_16x16x64_i8 v[70:73], v[182:185], v[106:109], v[2:5]
	v_mfma_i32_16x16x64_i8 v[2:5], v[186:189], v[102:105], v[66:69]
	v_mfma_i32_16x16x64_i8 v[66:69], v[190:193], v[106:109], v[2:5]
	v_mfma_i32_16x16x64_i8 v[2:5], v[178:181], v[110:113], v[54:57]
	v_mfma_i32_16x16x64_i8 v[54:57], v[182:185], v[214:217], v[2:5]
	v_mfma_i32_16x16x64_i8 v[2:5], v[186:189], v[110:113], v[50:53]
	v_mfma_i32_16x16x64_i8 v[50:53], v[190:193], v[214:217], v[2:5]
	v_mfma_i32_16x16x64_i8 v[2:5], v[178:181], v[218:221], v[18:21]
	v_mfma_i32_16x16x64_i8 v[38:41], v[182:185], v[222:225], v[2:5]
	v_mfma_i32_16x16x64_i8 v[2:5], v[186:189], v[218:221], v[22:25]
	v_mfma_i32_16x16x64_i8 v[34:37], v[190:193], v[222:225], v[2:5]
	s_barrier
	s_add_i32 s80, s80, 2
	s_add_u32 s4, s4, 0x100
	s_addc_u32 s5, s5, 0
	s_add_u32 s78, s78, 0x100
	s_addc_u32 s79, s79, 0
	s_cmp_gt_u32 s80, 29

.LBB0_1231:
	s_ashr_i32 s23, s22, 31
	s_lshl_b64 s[24:25], s[22:23], 20
	s_add_u32 s24, s17, s24
	s_addc_u32 s25, s36, s25
	s_and_b64 s[26:27], s[0:1], exec
	s_cselect_b32 s23, s25, s29
	s_cselect_b32 s66, s24, s28
	s_ashr_i32 s15, s14, 31
	s_lshl_b64 s[26:27], s[14:15], 20
	s_add_u32 s26, s37, s26
	s_addc_u32 s27, s38, s27
	s_and_b64 s[34:35], s[0:1], exec
	s_cselect_b32 s15, s27, s31
	s_cselect_b32 s67, s26, s30
	s_add_u32 s28, s28, 0x80080
	s_addc_u32 s29, s29, 0
	s_add_u32 s68, s30, 0x100
	s_addc_u32 s69, s31, 0
	s_mov_b32 s70, -2
	ds_read_b128 v[106:109], v197
	ds_read_b128 v[114:117], v197 offset:1024
	ds_read_b128 v[122:125], v197 offset:2048
	ds_read_b128 v[130:133], v197 offset:3072
	ds_read_b128 v[146:149], v201
	ds_read_b128 v[150:153], v201 offset:1024
	ds_read_b128 v[154:157], v201 offset:2048
	ds_read_b128 v[158:161], v201 offset:3072
	s_add_u32 s30, s28, 0xfff80080
	s_addc_u32 s31, s29, -1
	s_cmp_eq_u32 s70, 28
	s_cselect_b32 s35, s23, s31
	s_cselect_b32 s34, s66, s30
	s_cselect_b32 s31, s15, s69
	s_cselect_b32 s30, s67, s68
	v_lshl_add_u64 v[194:195], s[28:29], 0, v[174:175]
	s_add_i32 m0, s19, 0xc000
	ds_read_b128 v[162:165], v204
	ds_read_b128 v[182:185], v204 offset:1024
	ds_read_b128 v[186:189], v204 offset:2048
	ds_read_b128 v[206:209], v204 offset:3072
	ds_read_b128 v[210:213], v204 offset:4096
	ds_read_b128 v[214:217], v204 offset:5120
	ds_read_b128 v[218:221], v204 offset:6144
	ds_read_b128 v[222:225], v204 offset:7168
	global_load_lds_dwordx4 v[194:195], off
	v_lshl_add_u64 v[194:195], s[28:29], 0, v[176:177]
	s_add_i32 m0, s19, 0xe000
	s_nop 0
	global_load_lds_dwordx4 v[194:195], off
	s_waitcnt vmcnt(8)
	s_waitcnt lgkmcnt(0)
	s_barrier
	v_mfma_i32_16x16x64_i8 v[142:145], v[106:109], v[162:165], 0
	v_mfma_i32_16x16x64_i8 v[138:141], v[122:125], v[162:165], 0
	v_mfma_i32_16x16x64_i8 v[118:121], v[106:109], v[186:189], 0
	v_mfma_i32_16x16x64_i8 v[110:113], v[122:125], v[186:189], 0
	v_mfma_i32_16x16x64_i8 v[94:97], v[106:109], v[210:213], 0
	v_mfma_i32_16x16x64_i8 v[90:93], v[122:125], v[210:213], 0
	v_mfma_i32_16x16x64_i8 v[78:81], v[106:109], v[218:221], 0
	v_mfma_i32_16x16x64_i8 v[74:77], v[122:125], v[218:221], 0
	v_mfma_i32_16x16x64_i8 v[142:145], v[114:117], v[182:185], v[142:145]
	v_mfma_i32_16x16x64_i8 v[138:141], v[130:133], v[182:185], v[138:141]
	v_mfma_i32_16x16x64_i8 v[118:121], v[114:117], v[206:209], v[118:121]
	v_mfma_i32_16x16x64_i8 v[110:113], v[130:133], v[206:209], v[110:113]
	v_mfma_i32_16x16x64_i8 v[94:97], v[114:117], v[214:217], v[94:97]
	v_mfma_i32_16x16x64_i8 v[90:93], v[130:133], v[214:217], v[90:93]
	v_mfma_i32_16x16x64_i8 v[78:81], v[114:117], v[222:225], v[78:81]
	v_mfma_i32_16x16x64_i8 v[74:77], v[130:133], v[222:225], v[74:77]
	v_mfma_i32_16x16x64_i8 v[134:137], v[146:149], v[162:165], 0
	v_mfma_i32_16x16x64_i8 v[126:129], v[154:157], v[162:165], 0
	v_mfma_i32_16x16x64_i8 v[102:105], v[146:149], v[186:189], 0
	v_mfma_i32_16x16x64_i8 v[98:101], v[154:157], v[186:189], 0
	v_mfma_i32_16x16x64_i8 v[86:89], v[146:149], v[210:213], 0
	v_mfma_i32_16x16x64_i8 v[82:85], v[154:157], v[210:213], 0
	v_mfma_i32_16x16x64_i8 v[70:73], v[146:149], v[218:221], 0
	v_mfma_i32_16x16x64_i8 v[66:69], v[154:157], v[218:221], 0
	v_mfma_i32_16x16x64_i8 v[134:137], v[150:153], v[182:185], v[134:137]
	v_mfma_i32_16x16x64_i8 v[126:129], v[158:161], v[182:185], v[126:129]
	v_mfma_i32_16x16x64_i8 v[102:105], v[150:153], v[206:209], v[102:105]
	v_mfma_i32_16x16x64_i8 v[98:101], v[158:161], v[206:209], v[98:101]
	v_mfma_i32_16x16x64_i8 v[86:89], v[150:153], v[214:217], v[86:89]
	v_mfma_i32_16x16x64_i8 v[82:85], v[158:161], v[214:217], v[82:85]
	v_mfma_i32_16x16x64_i8 v[70:73], v[150:153], v[222:225], v[70:73]
	v_mfma_i32_16x16x64_i8 v[66:69], v[158:161], v[222:225], v[66:69]
	s_barrier
	s_add_i32 s71, s63, s39
	v_lshl_add_u64 v[194:195], s[30:31], 0, v[168:169]
	s_mov_b32 m0, s71
	ds_read_b128 v[162:165], v204 offset:16384
	ds_read_b128 v[182:185], v204 offset:17408
	ds_read_b128 v[186:189], v204 offset:18432
	ds_read_b128 v[206:209], v204 offset:19456
	ds_read_b128 v[210:213], v204 offset:20480
	ds_read_b128 v[214:217], v204 offset:21504
	ds_read_b128 v[218:221], v204 offset:22528
	ds_read_b128 v[222:225], v204 offset:23552
	global_load_lds_dwordx4 v[194:195], off
	s_add_i32 m0, s71, 0x2000
	s_add_u32 s72, s30, 0x80000
	v_lshl_add_u64 v[198:199], s[30:31], 0, v[172:173]
	s_addc_u32 s73, s31, 0
	s_add_i32 s71, s64, s39
	global_load_lds_dwordx4 v[198:199], off
	v_lshl_add_u64 v[202:203], s[72:73], 0, v[168:169]
	s_mov_b32 m0, s71
	v_lshl_add_u64 v[226:227], s[34:35], 0, v[170:171]
	global_load_lds_dwordx4 v[202:203], off
	v_lshl_add_u64 v[202:203], s[72:73], 0, v[172:173]
	s_add_i32 m0, s71, 0x2000
	s_nop 0
	global_load_lds_dwordx4 v[202:203], off
	v_lshl_add_u64 v[202:203], s[34:35], 0, v[166:167]
	s_mov_b32 m0, s19
	s_nop 0
	global_load_lds_dwordx4 v[202:203], off
	s_mov_b32 m0, s40
	s_nop 0
	global_load_lds_dwordx4 v[226:227], off
	s_waitcnt vmcnt(8)
	s_waitcnt lgkmcnt(0)
	s_barrier
	v_mfma_i32_16x16x64_i8 v[62:65], v[106:109], v[162:165], 0
	v_mfma_i32_16x16x64_i8 v[58:61], v[122:125], v[162:165], 0
	v_mfma_i32_16x16x64_i8 v[46:49], v[106:109], v[186:189], 0
	v_mfma_i32_16x16x64_i8 v[42:45], v[122:125], v[186:189], 0
	v_mfma_i32_16x16x64_i8 v[30:33], v[106:109], v[210:213], 0
	v_mfma_i32_16x16x64_i8 v[26:29], v[122:125], v[210:213], 0
	v_mfma_i32_16x16x64_i8 v[14:17], v[106:109], v[218:221], 0
	v_mfma_i32_16x16x64_i8 v[10:13], v[122:125], v[218:221], 0
	v_mfma_i32_16x16x64_i8 v[62:65], v[114:117], v[182:185], v[62:65]
	v_mfma_i32_16x16x64_i8 v[58:61], v[130:133], v[182:185], v[58:61]
	v_mfma_i32_16x16x64_i8 v[46:49], v[114:117], v[206:209], v[46:49]
	v_mfma_i32_16x16x64_i8 v[42:45], v[130:133], v[206:209], v[42:45]
	v_mfma_i32_16x16x64_i8 v[30:33], v[114:117], v[214:217], v[30:33]
	v_mfma_i32_16x16x64_i8 v[26:29], v[130:133], v[214:217], v[26:29]
	v_mfma_i32_16x16x64_i8 v[14:17], v[114:117], v[222:225], v[14:17]
	v_mfma_i32_16x16x64_i8 v[10:13], v[130:133], v[222:225], v[10:13]
	v_mfma_i32_16x16x64_i8 v[54:57], v[146:149], v[162:165], 0
	v_mfma_i32_16x16x64_i8 v[50:53], v[154:157], v[162:165], 0
	v_mfma_i32_16x16x64_i8 v[38:41], v[146:149], v[186:189], 0
	v_mfma_i32_16x16x64_i8 v[34:37], v[154:157], v[186:189], 0
	v_mfma_i32_16x16x64_i8 v[22:25], v[146:149], v[210:213], 0
	v_mfma_i32_16x16x64_i8 v[18:21], v[154:157], v[210:213], 0
	v_mfma_i32_16x16x64_i8 v[6:9], v[146:149], v[218:221], 0
	v_mfma_i32_16x16x64_i8 v[2:5], v[154:157], v[218:221], 0
	v_mfma_i32_16x16x64_i8 v[54:57], v[150:153], v[182:185], v[54:57]
	v_mfma_i32_16x16x64_i8 v[50:53], v[158:161], v[182:185], v[50:53]
	v_mfma_i32_16x16x64_i8 v[38:41], v[150:153], v[206:209], v[38:41]
	v_mfma_i32_16x16x64_i8 v[34:37], v[158:161], v[206:209], v[34:37]
	v_mfma_i32_16x16x64_i8 v[22:25], v[150:153], v[214:217], v[22:25]
	v_mfma_i32_16x16x64_i8 v[18:21], v[158:161], v[214:217], v[18:21]
	v_mfma_i32_16x16x64_i8 v[6:9], v[150:153], v[222:225], v[6:9]
	v_mfma_i32_16x16x64_i8 v[2:5], v[158:161], v[222:225], v[2:5]
	s_barrier
	s_add_i32 s71, 0, 0x18000
	s_add_i32 s72, 0, 0x1c000
	v_add_u32_e32 v130, s71, v193
	v_add_u32_e32 v158, s72, v193
	ds_read_b128 v[106:109], v130
	ds_read_b128 v[114:117], v130 offset:1024
	ds_read_b128 v[122:125], v130 offset:2048
	ds_read_b128 v[130:133], v130 offset:3072
	ds_read_b128 v[146:149], v158
	ds_read_b128 v[150:153], v158 offset:1024
	ds_read_b128 v[154:157], v158 offset:2048
	ds_read_b128 v[158:161], v158 offset:3072
	s_add_u32 s34, s34, 0x80000
	s_addc_u32 s35, s35, 0
	s_mov_b32 m0, s41
	v_lshl_add_u64 v[228:229], s[34:35], 0, v[166:167]
	ds_read_b128 v[162:165], v204 offset:32768
	ds_read_b128 v[182:185], v204 offset:33792
	ds_read_b128 v[186:189], v204 offset:34816
	ds_read_b128 v[206:209], v204 offset:35840
	ds_read_b128 v[210:213], v204 offset:36864
	ds_read_b128 v[214:217], v204 offset:37888
	ds_read_b128 v[218:221], v204 offset:38912
	ds_read_b128 v[222:225], v204 offset:39936
	global_load_lds_dwordx4 v[228:229], off
	v_lshl_add_u64 v[228:229], s[34:35], 0, v[170:171]
	s_mov_b32 m0, s42
	s_nop 0
	global_load_lds_dwordx4 v[228:229], off
	s_waitcnt vmcnt(8)
	s_waitcnt lgkmcnt(0)
	s_barrier
	v_mfma_i32_16x16x64_i8 v[142:145], v[106:109], v[162:165], v[142:145]
	v_mfma_i32_16x16x64_i8 v[138:141], v[122:125], v[162:165], v[138:141]
	v_mfma_i32_16x16x64_i8 v[118:121], v[106:109], v[186:189], v[118:121]
	v_mfma_i32_16x16x64_i8 v[110:113], v[122:125], v[186:189], v[110:113]
	v_mfma_i32_16x16x64_i8 v[94:97], v[106:109], v[210:213], v[94:97]
	v_mfma_i32_16x16x64_i8 v[90:93], v[122:125], v[210:213], v[90:93]
	v_mfma_i32_16x16x64_i8 v[78:81], v[106:109], v[218:221], v[78:81]
	v_mfma_i32_16x16x64_i8 v[74:77], v[122:125], v[218:221], v[74:77]
	v_mfma_i32_16x16x64_i8 v[142:145], v[114:117], v[182:185], v[142:145]
	v_mfma_i32_16x16x64_i8 v[138:141], v[130:133], v[182:185], v[138:141]
	v_mfma_i32_16x16x64_i8 v[118:121], v[114:117], v[206:209], v[118:121]
	v_mfma_i32_16x16x64_i8 v[110:113], v[130:133], v[206:209], v[110:113]
	v_mfma_i32_16x16x64_i8 v[94:97], v[114:117], v[214:217], v[94:97]
	v_mfma_i32_16x16x64_i8 v[90:93], v[130:133], v[214:217], v[90:93]
	v_mfma_i32_16x16x64_i8 v[78:81], v[114:117], v[222:225], v[78:81]
	v_mfma_i32_16x16x64_i8 v[74:77], v[130:133], v[222:225], v[74:77]
	v_mfma_i32_16x16x64_i8 v[134:137], v[146:149], v[162:165], v[134:137]
	v_mfma_i32_16x16x64_i8 v[126:129], v[154:157], v[162:165], v[126:129]
	v_mfma_i32_16x16x64_i8 v[102:105], v[146:149], v[186:189], v[102:105]
	v_mfma_i32_16x16x64_i8 v[98:101], v[154:157], v[186:189], v[98:101]
	v_mfma_i32_16x16x64_i8 v[86:89], v[146:149], v[210:213], v[86:89]
	v_mfma_i32_16x16x64_i8 v[82:85], v[154:157], v[210:213], v[82:85]
	v_mfma_i32_16x16x64_i8 v[70:73], v[146:149], v[218:221], v[70:73]
	v_mfma_i32_16x16x64_i8 v[66:69], v[154:157], v[218:221], v[66:69]
	v_mfma_i32_16x16x64_i8 v[134:137], v[150:153], v[182:185], v[134:137]
	v_mfma_i32_16x16x64_i8 v[126:129], v[158:161], v[182:185], v[126:129]
	v_mfma_i32_16x16x64_i8 v[102:105], v[150:153], v[206:209], v[102:105]
	v_mfma_i32_16x16x64_i8 v[98:101], v[158:161], v[206:209], v[98:101]
	v_mfma_i32_16x16x64_i8 v[86:89], v[150:153], v[214:217], v[86:89]
	v_mfma_i32_16x16x64_i8 v[82:85], v[158:161], v[214:217], v[82:85]
	v_mfma_i32_16x16x64_i8 v[70:73], v[150:153], v[222:225], v[70:73]
	v_mfma_i32_16x16x64_i8 v[66:69], v[158:161], v[222:225], v[66:69]
	s_barrier
	s_add_i32 s34, s71, s39
	v_lshl_add_u64 v[194:195], v[194:195], 0, s[10:11]
	s_mov_b32 m0, s34
	ds_read_b128 v[162:165], v204 offset:49152
	ds_read_b128 v[182:185], v204 offset:50176
	ds_read_b128 v[186:189], v204 offset:51200
	ds_read_b128 v[206:209], v204 offset:52224
	ds_read_b128 v[210:213], v204 offset:53248
	ds_read_b128 v[214:217], v204 offset:54272
	ds_read_b128 v[218:221], v204 offset:55296
	ds_read_b128 v[222:225], v204 offset:56320
	global_load_lds_dwordx4 v[194:195], off
	s_add_i32 m0, s34, 0x2000
	s_add_u32 s30, s30, 0x80080
	v_lshl_add_u64 v[194:195], v[198:199], 0, s[10:11]
	s_addc_u32 s31, s31, 0
	s_add_i32 s34, s72, s39
	global_load_lds_dwordx4 v[194:195], off
	v_lshl_add_u64 v[194:195], s[30:31], 0, v[168:169]
	s_mov_b32 m0, s34
	s_nop 0
	global_load_lds_dwordx4 v[194:195], off
	v_lshl_add_u64 v[194:195], s[30:31], 0, v[172:173]
	s_add_i32 m0, s34, 0x2000
	s_nop 0
	global_load_lds_dwordx4 v[194:195], off
	v_lshl_add_u64 v[194:195], v[202:203], 0, s[10:11]
	s_mov_b32 m0, s60
	s_nop 0
	global_load_lds_dwordx4 v[194:195], off
	v_lshl_add_u64 v[194:195], v[226:227], 0, s[10:11]
	s_mov_b32 m0, s61
	s_nop 0
	global_load_lds_dwordx4 v[194:195], off
	s_waitcnt vmcnt(8)
	s_waitcnt lgkmcnt(0)
	s_barrier
	v_mfma_i32_16x16x64_i8 v[62:65], v[106:109], v[162:165], v[62:65]
	v_mfma_i32_16x16x64_i8 v[58:61], v[122:125], v[162:165], v[58:61]
	v_mfma_i32_16x16x64_i8 v[46:49], v[106:109], v[186:189], v[46:49]
	v_mfma_i32_16x16x64_i8 v[42:45], v[122:125], v[186:189], v[42:45]
	v_mfma_i32_16x16x64_i8 v[30:33], v[106:109], v[210:213], v[30:33]
	v_mfma_i32_16x16x64_i8 v[26:29], v[122:125], v[210:213], v[26:29]
	v_mfma_i32_16x16x64_i8 v[14:17], v[106:109], v[218:221], v[14:17]
	v_mfma_i32_16x16x64_i8 v[10:13], v[122:125], v[218:221], v[10:13]
	v_mfma_i32_16x16x64_i8 v[62:65], v[114:117], v[182:185], v[62:65]
	v_mfma_i32_16x16x64_i8 v[58:61], v[130:133], v[182:185], v[58:61]
	v_mfma_i32_16x16x64_i8 v[46:49], v[114:117], v[206:209], v[46:49]
	v_mfma_i32_16x16x64_i8 v[42:45], v[130:133], v[206:209], v[42:45]
	v_mfma_i32_16x16x64_i8 v[30:33], v[114:117], v[214:217], v[30:33]
	v_mfma_i32_16x16x64_i8 v[26:29], v[130:133], v[214:217], v[26:29]
	v_mfma_i32_16x16x64_i8 v[14:17], v[114:117], v[222:225], v[14:17]
	v_mfma_i32_16x16x64_i8 v[10:13], v[130:133], v[222:225], v[10:13]
	v_mfma_i32_16x16x64_i8 v[54:57], v[146:149], v[162:165], v[54:57]
	v_mfma_i32_16x16x64_i8 v[50:53], v[154:157], v[162:165], v[50:53]
	v_mfma_i32_16x16x64_i8 v[38:41], v[146:149], v[186:189], v[38:41]
	v_mfma_i32_16x16x64_i8 v[34:37], v[154:157], v[186:189], v[34:37]
	v_mfma_i32_16x16x64_i8 v[22:25], v[146:149], v[210:213], v[22:25]
	v_mfma_i32_16x16x64_i8 v[18:21], v[154:157], v[210:213], v[18:21]
	v_mfma_i32_16x16x64_i8 v[6:9], v[146:149], v[218:221], v[6:9]
	v_mfma_i32_16x16x64_i8 v[2:5], v[154:157], v[218:221], v[2:5]
	v_mfma_i32_16x16x64_i8 v[54:57], v[150:153], v[182:185], v[54:57]
	v_mfma_i32_16x16x64_i8 v[50:53], v[158:161], v[182:185], v[50:53]
	v_mfma_i32_16x16x64_i8 v[38:41], v[150:153], v[206:209], v[38:41]
	v_mfma_i32_16x16x64_i8 v[34:37], v[158:161], v[206:209], v[34:37]
	v_mfma_i32_16x16x64_i8 v[22:25], v[150:153], v[214:217], v[22:25]
	v_mfma_i32_16x16x64_i8 v[18:21], v[158:161], v[214:217], v[18:21]
	v_mfma_i32_16x16x64_i8 v[6:9], v[150:153], v[222:225], v[6:9]
	v_mfma_i32_16x16x64_i8 v[2:5], v[158:161], v[222:225], v[2:5]
	s_barrier
	s_add_i32 s70, s70, 2
	s_add_u32 s28, s28, 0x100
	s_addc_u32 s29, s29, 0
	s_add_u32 s68, s68, 0x100
	s_addc_u32 s69, s69, 0
	s_cmp_gt_u32 s70, 29

.LBB0_1366:
	s_ashr_i32 s35, s34, 31
	s_lshl_b64 s[18:19], s[34:35], 20
	s_add_u32 s36, s29, s18
	s_addc_u32 s37, s60, s19
	s_and_b64 s[18:19], s[2:3], exec
	s_cselect_b32 s35, s37, s5
	s_cselect_b32 s43, s36, s4
	s_ashr_i32 s31, s30, 31
	s_lshl_b64 s[18:19], s[30:31], 20
	s_add_u32 s38, s61, s18
	s_addc_u32 s39, s62, s19
	s_and_b64 s[18:19], s[2:3], exec
	s_cselect_b32 s31, s39, s7
	s_cselect_b32 vcc_lo, s38, s6
	s_add_u32 vcc_hi, s6, 0x100
	s_addc_u32 s79, s7, 0
	s_mov_b32 s80, -2
	ds_read_b128 v[130:133], v234
	ds_read_b128 v[134:137], v234 offset:1024
	ds_read_b128 v[162:165], v234 offset:2048
	ds_read_b128 v[166:169], v234 offset:3072
	ds_read_b128 v[170:173], v235
	ds_read_b128 v[174:177], v235 offset:1024
	ds_read_b128 v[178:181], v235 offset:2048
	ds_read_b128 v[182:185], v235 offset:3072
	s_add_u32 s6, s4, 0x100
	s_addc_u32 s7, s5, 0
	s_cmp_eq_u32 s80, 28
	s_cselect_b32 s57, s35, s7
	s_cselect_b32 s56, s43, s6
	s_cselect_b32 s19, s31, s79
	s_cselect_b32 s18, vcc_lo, vcc_hi
	v_lshl_add_u64 v[218:219], s[4:5], 0, v[154:155]
	s_add_i32 m0, s65, 0xc000
	ds_read_b128 v[186:189], v236
	ds_read_b128 v[190:193], v236 offset:1024
	ds_read_b128 v[194:197], v236 offset:2048
	ds_read_b128 v[198:201], v236 offset:3072
	ds_read_b128 v[202:205], v236 offset:4096
	ds_read_b128 v[206:209], v236 offset:5120
	ds_read_b128 v[210:213], v236 offset:6144
	ds_read_b128 v[214:217], v236 offset:7168
	global_load_lds_dwordx4 v[218:219], off
	v_lshl_add_u64 v[218:219], s[4:5], 0, v[156:157]
	s_add_i32 m0, s65, 0xe000
	s_nop 0
	global_load_lds_dwordx4 v[218:219], off
	s_waitcnt vmcnt(8)
	s_waitcnt lgkmcnt(0)
	s_barrier
	v_mfma_i32_16x16x64_i8 v[118:121], v[130:133], v[186:189], 0
	v_mfma_i32_16x16x64_i8 v[102:105], v[162:165], v[186:189], 0
	v_mfma_i32_16x16x64_i8 v[114:117], v[130:133], v[194:197], 0
	v_mfma_i32_16x16x64_i8 v[98:101], v[162:165], v[194:197], 0
	v_mfma_i32_16x16x64_i8 v[126:129], v[130:133], v[202:205], 0
	v_mfma_i32_16x16x64_i8 v[110:113], v[162:165], v[202:205], 0
	v_mfma_i32_16x16x64_i8 v[122:125], v[130:133], v[210:213], 0
	v_mfma_i32_16x16x64_i8 v[106:109], v[162:165], v[210:213], 0
	v_mfma_i32_16x16x64_i8 v[118:121], v[134:137], v[190:193], v[118:121]
	v_mfma_i32_16x16x64_i8 v[102:105], v[166:169], v[190:193], v[102:105]
	v_mfma_i32_16x16x64_i8 v[114:117], v[134:137], v[198:201], v[114:117]
	v_mfma_i32_16x16x64_i8 v[98:101], v[166:169], v[198:201], v[98:101]
	v_mfma_i32_16x16x64_i8 v[126:129], v[134:137], v[206:209], v[126:129]
	v_mfma_i32_16x16x64_i8 v[110:113], v[166:169], v[206:209], v[110:113]
	v_mfma_i32_16x16x64_i8 v[122:125], v[134:137], v[214:217], v[122:125]
	v_mfma_i32_16x16x64_i8 v[106:109], v[166:169], v[214:217], v[106:109]
	v_mfma_i32_16x16x64_i8 v[86:89], v[170:173], v[186:189], 0
	v_mfma_i32_16x16x64_i8 v[70:73], v[178:181], v[186:189], 0
	v_mfma_i32_16x16x64_i8 v[82:85], v[170:173], v[194:197], 0
	v_mfma_i32_16x16x64_i8 v[66:69], v[178:181], v[194:197], 0
	v_mfma_i32_16x16x64_i8 v[94:97], v[170:173], v[202:205], 0
	v_mfma_i32_16x16x64_i8 v[78:81], v[178:181], v[202:205], 0
	v_mfma_i32_16x16x64_i8 v[90:93], v[170:173], v[210:213], 0
	v_mfma_i32_16x16x64_i8 v[74:77], v[178:181], v[210:213], 0
	v_mfma_i32_16x16x64_i8 v[86:89], v[174:177], v[190:193], v[86:89]
	v_mfma_i32_16x16x64_i8 v[70:73], v[182:185], v[190:193], v[70:73]
	v_mfma_i32_16x16x64_i8 v[82:85], v[174:177], v[198:201], v[82:85]
	v_mfma_i32_16x16x64_i8 v[66:69], v[182:185], v[198:201], v[66:69]
	v_mfma_i32_16x16x64_i8 v[94:97], v[174:177], v[206:209], v[94:97]
	v_mfma_i32_16x16x64_i8 v[78:81], v[182:185], v[206:209], v[78:81]
	v_mfma_i32_16x16x64_i8 v[90:93], v[174:177], v[214:217], v[90:93]
	v_mfma_i32_16x16x64_i8 v[74:77], v[182:185], v[214:217], v[74:77]
	s_barrier
	s_add_i32 s4, s97, s63
	v_lshl_add_u64 v[218:219], s[18:19], 0, v[144:145]
	s_mov_b32 m0, s4
	ds_read_b128 v[186:189], v236 offset:16384
	ds_read_b128 v[190:193], v236 offset:17408
	ds_read_b128 v[194:197], v236 offset:18432
	ds_read_b128 v[198:201], v236 offset:19456
	ds_read_b128 v[202:205], v236 offset:20480
	ds_read_b128 v[206:209], v236 offset:21504
	ds_read_b128 v[210:213], v236 offset:22528
	ds_read_b128 v[214:217], v236 offset:23552
	global_load_lds_dwordx4 v[218:219], off
	s_add_i32 m0, s4, 0x2000
	s_add_u32 s4, s18, 0x80000
	v_lshl_add_u64 v[220:221], s[18:19], 0, v[148:149]
	s_addc_u32 s5, s19, 0
	s_add_i32 s81, s0, s63
	global_load_lds_dwordx4 v[220:221], off
	v_lshl_add_u64 v[222:223], s[4:5], 0, v[144:145]
	s_mov_b32 m0, s81
	v_lshl_add_u64 v[224:225], s[56:57], 0, v[146:147]
	global_load_lds_dwordx4 v[222:223], off
	v_lshl_add_u64 v[222:223], s[4:5], 0, v[148:149]
	s_add_i32 m0, s81, 0x2000
	s_nop 0
	global_load_lds_dwordx4 v[222:223], off
	v_lshl_add_u64 v[222:223], s[56:57], 0, v[142:143]
	s_mov_b32 m0, s65
	s_nop 0
	global_load_lds_dwordx4 v[222:223], off
	s_mov_b32 m0, s66
	s_nop 0
	global_load_lds_dwordx4 v[224:225], off
	s_waitcnt vmcnt(8)
	s_waitcnt lgkmcnt(0)
	s_barrier
	v_mfma_i32_16x16x64_i8 v[54:57], v[130:133], v[186:189], 0
	v_mfma_i32_16x16x64_i8 v[18:21], v[162:165], v[186:189], 0
	v_mfma_i32_16x16x64_i8 v[50:53], v[130:133], v[194:197], 0
	v_mfma_i32_16x16x64_i8 v[22:25], v[162:165], v[194:197], 0
	v_mfma_i32_16x16x64_i8 v[62:65], v[130:133], v[202:205], 0
	v_mfma_i32_16x16x64_i8 v[30:33], v[162:165], v[202:205], 0
	v_mfma_i32_16x16x64_i8 v[58:61], v[130:133], v[210:213], 0
	v_mfma_i32_16x16x64_i8 v[26:29], v[162:165], v[210:213], 0
	v_mfma_i32_16x16x64_i8 v[54:57], v[134:137], v[190:193], v[54:57]
	v_mfma_i32_16x16x64_i8 v[18:21], v[166:169], v[190:193], v[18:21]
	v_mfma_i32_16x16x64_i8 v[50:53], v[134:137], v[198:201], v[50:53]
	v_mfma_i32_16x16x64_i8 v[22:25], v[166:169], v[198:201], v[22:25]
	v_mfma_i32_16x16x64_i8 v[62:65], v[134:137], v[206:209], v[62:65]
	v_mfma_i32_16x16x64_i8 v[30:33], v[166:169], v[206:209], v[30:33]
	v_mfma_i32_16x16x64_i8 v[58:61], v[134:137], v[214:217], v[58:61]
	v_mfma_i32_16x16x64_i8 v[26:29], v[166:169], v[214:217], v[26:29]
	v_mfma_i32_16x16x64_i8 v[46:49], v[170:173], v[186:189], 0
	v_mfma_i32_16x16x64_i8 v[14:17], v[178:181], v[186:189], 0
	v_mfma_i32_16x16x64_i8 v[42:45], v[170:173], v[194:197], 0
	v_mfma_i32_16x16x64_i8 v[10:13], v[178:181], v[194:197], 0
	v_mfma_i32_16x16x64_i8 v[38:41], v[170:173], v[202:205], 0
	v_mfma_i32_16x16x64_i8 v[6:9], v[178:181], v[202:205], 0
	v_mfma_i32_16x16x64_i8 v[34:37], v[170:173], v[210:213], 0
	v_mfma_i32_16x16x64_i8 v[2:5], v[178:181], v[210:213], 0
	v_mfma_i32_16x16x64_i8 v[46:49], v[174:177], v[190:193], v[46:49]
	v_mfma_i32_16x16x64_i8 v[14:17], v[182:185], v[190:193], v[14:17]
	v_mfma_i32_16x16x64_i8 v[42:45], v[174:177], v[198:201], v[42:45]
	v_mfma_i32_16x16x64_i8 v[10:13], v[182:185], v[198:201], v[10:13]
	v_mfma_i32_16x16x64_i8 v[38:41], v[174:177], v[206:209], v[38:41]
	v_mfma_i32_16x16x64_i8 v[6:9], v[182:185], v[206:209], v[6:9]
	v_mfma_i32_16x16x64_i8 v[34:37], v[174:177], v[214:217], v[34:37]
	v_mfma_i32_16x16x64_i8 v[2:5], v[182:185], v[214:217], v[2:5]
	s_barrier
	s_add_i32 s81, 0, 0x18000
	s_add_i32 s82, 0, 0x1c000
	v_add_u32_e32 v166, s81, v232
	v_add_u32_e32 v182, s82, v232
	ds_read_b128 v[130:133], v166
	ds_read_b128 v[134:137], v166 offset:1024
	ds_read_b128 v[162:165], v166 offset:2048
	ds_read_b128 v[166:169], v166 offset:3072
	ds_read_b128 v[170:173], v182
	ds_read_b128 v[174:177], v182 offset:1024
	ds_read_b128 v[178:181], v182 offset:2048
	ds_read_b128 v[182:185], v182 offset:3072
	s_add_u32 s4, s56, 0x80000
	s_addc_u32 s5, s57, 0
	s_mov_b32 m0, s67
	v_lshl_add_u64 v[226:227], s[4:5], 0, v[142:143]
	ds_read_b128 v[186:189], v236 offset:32768
	ds_read_b128 v[190:193], v236 offset:33792
	ds_read_b128 v[194:197], v236 offset:34816
	ds_read_b128 v[198:201], v236 offset:35840
	ds_read_b128 v[202:205], v236 offset:36864
	ds_read_b128 v[206:209], v236 offset:37888
	ds_read_b128 v[210:213], v236 offset:38912
	ds_read_b128 v[214:217], v236 offset:39936
	global_load_lds_dwordx4 v[226:227], off
	v_lshl_add_u64 v[226:227], s[4:5], 0, v[146:147]
	s_mov_b32 m0, s68
	s_nop 0
	global_load_lds_dwordx4 v[226:227], off
	s_waitcnt vmcnt(8)
	s_waitcnt lgkmcnt(0)
	s_barrier
	v_mfma_i32_16x16x64_i8 v[118:121], v[130:133], v[186:189], v[118:121]
	v_mfma_i32_16x16x64_i8 v[102:105], v[162:165], v[186:189], v[102:105]
	v_mfma_i32_16x16x64_i8 v[114:117], v[130:133], v[194:197], v[114:117]
	v_mfma_i32_16x16x64_i8 v[98:101], v[162:165], v[194:197], v[98:101]
	v_mfma_i32_16x16x64_i8 v[126:129], v[130:133], v[202:205], v[126:129]
	v_mfma_i32_16x16x64_i8 v[110:113], v[162:165], v[202:205], v[110:113]
	v_mfma_i32_16x16x64_i8 v[122:125], v[130:133], v[210:213], v[122:125]
	v_mfma_i32_16x16x64_i8 v[106:109], v[162:165], v[210:213], v[106:109]
	v_mfma_i32_16x16x64_i8 v[118:121], v[134:137], v[190:193], v[118:121]
	v_mfma_i32_16x16x64_i8 v[102:105], v[166:169], v[190:193], v[102:105]
	v_mfma_i32_16x16x64_i8 v[114:117], v[134:137], v[198:201], v[114:117]
	v_mfma_i32_16x16x64_i8 v[98:101], v[166:169], v[198:201], v[98:101]
	v_mfma_i32_16x16x64_i8 v[126:129], v[134:137], v[206:209], v[126:129]
	v_mfma_i32_16x16x64_i8 v[110:113], v[166:169], v[206:209], v[110:113]
	v_mfma_i32_16x16x64_i8 v[122:125], v[134:137], v[214:217], v[122:125]
	v_mfma_i32_16x16x64_i8 v[106:109], v[166:169], v[214:217], v[106:109]
	v_mfma_i32_16x16x64_i8 v[86:89], v[170:173], v[186:189], v[86:89]
	v_mfma_i32_16x16x64_i8 v[70:73], v[178:181], v[186:189], v[70:73]
	v_mfma_i32_16x16x64_i8 v[82:85], v[170:173], v[194:197], v[82:85]
	v_mfma_i32_16x16x64_i8 v[66:69], v[178:181], v[194:197], v[66:69]
	v_mfma_i32_16x16x64_i8 v[94:97], v[170:173], v[202:205], v[94:97]
	v_mfma_i32_16x16x64_i8 v[78:81], v[178:181], v[202:205], v[78:81]
	v_mfma_i32_16x16x64_i8 v[90:93], v[170:173], v[210:213], v[90:93]
	v_mfma_i32_16x16x64_i8 v[74:77], v[178:181], v[210:213], v[74:77]
	v_mfma_i32_16x16x64_i8 v[86:89], v[174:177], v[190:193], v[86:89]
	v_mfma_i32_16x16x64_i8 v[70:73], v[182:185], v[190:193], v[70:73]
	v_mfma_i32_16x16x64_i8 v[82:85], v[174:177], v[198:201], v[82:85]
	v_mfma_i32_16x16x64_i8 v[66:69], v[182:185], v[198:201], v[66:69]
	v_mfma_i32_16x16x64_i8 v[94:97], v[174:177], v[206:209], v[94:97]
	v_mfma_i32_16x16x64_i8 v[78:81], v[182:185], v[206:209], v[78:81]
	v_mfma_i32_16x16x64_i8 v[90:93], v[174:177], v[214:217], v[90:93]
	v_mfma_i32_16x16x64_i8 v[74:77], v[182:185], v[214:217], v[74:77]
	s_barrier
	s_add_i32 s4, s81, s63
	v_lshl_add_u64 v[218:219], v[218:219], 0, s[22:23]
	s_mov_b32 m0, s4
	ds_read_b128 v[186:189], v236 offset:49152
	ds_read_b128 v[190:193], v236 offset:50176
	ds_read_b128 v[194:197], v236 offset:51200
	ds_read_b128 v[198:201], v236 offset:52224
	ds_read_b128 v[202:205], v236 offset:53248
	ds_read_b128 v[206:209], v236 offset:54272
	ds_read_b128 v[210:213], v236 offset:55296
	ds_read_b128 v[214:217], v236 offset:56320
	global_load_lds_dwordx4 v[218:219], off
	s_add_i32 m0, s4, 0x2000
	s_add_u32 s4, s18, 0x80080
	v_lshl_add_u64 v[218:219], v[220:221], 0, s[22:23]
	s_addc_u32 s5, s19, 0
	s_add_i32 s18, s82, s63
	global_load_lds_dwordx4 v[218:219], off
	v_lshl_add_u64 v[218:219], s[4:5], 0, v[144:145]
	s_mov_b32 m0, s18
	s_nop 0
	global_load_lds_dwordx4 v[218:219], off
	v_lshl_add_u64 v[218:219], s[4:5], 0, v[148:149]
	s_add_i32 m0, s18, 0x2000
	s_nop 0
	global_load_lds_dwordx4 v[218:219], off
	v_lshl_add_u64 v[218:219], v[222:223], 0, s[22:23]
	s_mov_b32 m0, s77
	s_nop 0
	global_load_lds_dwordx4 v[218:219], off
	v_lshl_add_u64 v[218:219], v[224:225], 0, s[22:23]
	s_mov_b32 m0, s78
	s_nop 0
	global_load_lds_dwordx4 v[218:219], off
	s_waitcnt vmcnt(8)
	s_waitcnt lgkmcnt(0)
	s_barrier
	v_mfma_i32_16x16x64_i8 v[54:57], v[130:133], v[186:189], v[54:57]
	v_mfma_i32_16x16x64_i8 v[18:21], v[162:165], v[186:189], v[18:21]
	v_mfma_i32_16x16x64_i8 v[50:53], v[130:133], v[194:197], v[50:53]
	v_mfma_i32_16x16x64_i8 v[22:25], v[162:165], v[194:197], v[22:25]
	v_mfma_i32_16x16x64_i8 v[62:65], v[130:133], v[202:205], v[62:65]
	v_mfma_i32_16x16x64_i8 v[30:33], v[162:165], v[202:205], v[30:33]
	v_mfma_i32_16x16x64_i8 v[58:61], v[130:133], v[210:213], v[58:61]
	v_mfma_i32_16x16x64_i8 v[26:29], v[162:165], v[210:213], v[26:29]
	v_mfma_i32_16x16x64_i8 v[54:57], v[134:137], v[190:193], v[54:57]
	v_mfma_i32_16x16x64_i8 v[18:21], v[166:169], v[190:193], v[18:21]
	v_mfma_i32_16x16x64_i8 v[50:53], v[134:137], v[198:201], v[50:53]
	v_mfma_i32_16x16x64_i8 v[22:25], v[166:169], v[198:201], v[22:25]
	v_mfma_i32_16x16x64_i8 v[62:65], v[134:137], v[206:209], v[62:65]
	v_mfma_i32_16x16x64_i8 v[30:33], v[166:169], v[206:209], v[30:33]
	v_mfma_i32_16x16x64_i8 v[58:61], v[134:137], v[214:217], v[58:61]
	v_mfma_i32_16x16x64_i8 v[26:29], v[166:169], v[214:217], v[26:29]
	v_mfma_i32_16x16x64_i8 v[46:49], v[170:173], v[186:189], v[46:49]
	v_mfma_i32_16x16x64_i8 v[14:17], v[178:181], v[186:189], v[14:17]
	v_mfma_i32_16x16x64_i8 v[42:45], v[170:173], v[194:197], v[42:45]
	v_mfma_i32_16x16x64_i8 v[10:13], v[178:181], v[194:197], v[10:13]
	v_mfma_i32_16x16x64_i8 v[38:41], v[170:173], v[202:205], v[38:41]
	v_mfma_i32_16x16x64_i8 v[6:9], v[178:181], v[202:205], v[6:9]
	v_mfma_i32_16x16x64_i8 v[34:37], v[170:173], v[210:213], v[34:37]
	v_mfma_i32_16x16x64_i8 v[2:5], v[178:181], v[210:213], v[2:5]
	v_mfma_i32_16x16x64_i8 v[46:49], v[174:177], v[190:193], v[46:49]
	v_mfma_i32_16x16x64_i8 v[14:17], v[182:185], v[190:193], v[14:17]
	v_mfma_i32_16x16x64_i8 v[42:45], v[174:177], v[198:201], v[42:45]
	v_mfma_i32_16x16x64_i8 v[10:13], v[182:185], v[198:201], v[10:13]
	v_mfma_i32_16x16x64_i8 v[38:41], v[174:177], v[206:209], v[38:41]
	v_mfma_i32_16x16x64_i8 v[6:9], v[182:185], v[206:209], v[6:9]
	v_mfma_i32_16x16x64_i8 v[34:37], v[174:177], v[214:217], v[34:37]
	v_mfma_i32_16x16x64_i8 v[2:5], v[182:185], v[214:217], v[2:5]
	s_barrier
	s_add_i32 s80, s80, 2
	s_add_u32 vcc_hi, vcc_hi, 0x100
	s_addc_u32 s79, s79, 0
	s_cmp_gt_u32 s80, 29
	s_mov_b64 s[4:5], s[6:7]

.LBB0_1553:
	s_add_u32 s64, s26, 0x100
	s_addc_u32 s65, s27, 0
	s_mov_b32 s66, -2
	s_waitcnt lgkmcnt(0)
	ds_read_b128 v[114:117], v247
	ds_read_b128 v[118:121], v247 offset:1024
	ds_read_b128 v[126:129], v247 offset:2048
	ds_read_b128 v[134:137], v247 offset:3072
	ds_read_b128 v[138:141], v248
	ds_read_b128 v[142:145], v248 offset:1024
	ds_read_b128 v[154:157], v248 offset:2048
	ds_read_b128 v[158:161], v248 offset:3072
	s_add_u32 s4, s18, 0x100
	s_addc_u32 s5, s19, 0
	s_cmpk_eq_i32 s66, 0xdc
	s_cselect_b32 s29, s23, s5
	s_cselect_b32 s28, s22, s4
	s_cselect_b32 s27, s25, s65
	s_cselect_b32 s26, s24, s64
	v_lshl_add_u64 v[210:211], s[18:19], 0, v[202:203]
	s_add_i32 m0, s17, 0xc000
	ds_read_b128 v[162:165], v249
	ds_read_b128 v[166:169], v249 offset:1024
	ds_read_b128 v[170:173], v249 offset:2048
	ds_read_b128 v[174:177], v249 offset:3072
	ds_read_b128 v[178:181], v249 offset:4096
	ds_read_b128 v[182:185], v249 offset:5120
	ds_read_b128 v[186:189], v249 offset:6144
	ds_read_b128 v[190:193], v249 offset:7168
	global_load_lds_dwordx4 v[210:211], off
	v_lshl_add_u64 v[210:211], s[18:19], 0, v[204:205]
	s_add_i32 m0, s17, 0xe000
	s_nop 0
	global_load_lds_dwordx4 v[210:211], off
	s_waitcnt vmcnt(8)
	s_waitcnt lgkmcnt(0)
	s_barrier
	v_mfma_f32_16x16x32_bf16 v[150:153], v[114:117], v[162:165], 0
	v_mfma_f32_16x16x32_bf16 v[146:149], v[126:129], v[162:165], 0
	v_mfma_f32_16x16x32_bf16 v[110:113], v[114:117], v[170:173], 0
	v_mfma_f32_16x16x32_bf16 v[106:109], v[126:129], v[170:173], 0
	v_mfma_f32_16x16x32_bf16 v[94:97], v[114:117], v[178:181], 0
	v_mfma_f32_16x16x32_bf16 v[90:93], v[126:129], v[178:181], 0
	v_mfma_f32_16x16x32_bf16 v[78:81], v[114:117], v[186:189], 0
	v_mfma_f32_16x16x32_bf16 v[74:77], v[126:129], v[186:189], 0
	v_mfma_f32_16x16x32_bf16 v[150:153], v[118:121], v[166:169], v[150:153]
	v_mfma_f32_16x16x32_bf16 v[146:149], v[134:137], v[166:169], v[146:149]
	v_mfma_f32_16x16x32_bf16 v[110:113], v[118:121], v[174:177], v[110:113]
	v_mfma_f32_16x16x32_bf16 v[106:109], v[134:137], v[174:177], v[106:109]
	v_mfma_f32_16x16x32_bf16 v[94:97], v[118:121], v[182:185], v[94:97]
	v_mfma_f32_16x16x32_bf16 v[90:93], v[134:137], v[182:185], v[90:93]
	v_mfma_f32_16x16x32_bf16 v[78:81], v[118:121], v[190:193], v[78:81]
	v_mfma_f32_16x16x32_bf16 v[74:77], v[134:137], v[190:193], v[74:77]
	v_mfma_f32_16x16x32_bf16 v[130:133], v[138:141], v[162:165], 0
	v_mfma_f32_16x16x32_bf16 v[122:125], v[154:157], v[162:165], 0
	v_mfma_f32_16x16x32_bf16 v[102:105], v[138:141], v[170:173], 0
	v_mfma_f32_16x16x32_bf16 v[98:101], v[154:157], v[170:173], 0
	v_mfma_f32_16x16x32_bf16 v[86:89], v[138:141], v[178:181], 0
	v_mfma_f32_16x16x32_bf16 v[82:85], v[154:157], v[178:181], 0
	v_mfma_f32_16x16x32_bf16 v[70:73], v[138:141], v[186:189], 0
	v_mfma_f32_16x16x32_bf16 v[66:69], v[154:157], v[186:189], 0
	v_mfma_f32_16x16x32_bf16 v[130:133], v[142:145], v[166:169], v[130:133]
	v_mfma_f32_16x16x32_bf16 v[122:125], v[158:161], v[166:169], v[122:125]
	v_mfma_f32_16x16x32_bf16 v[102:105], v[142:145], v[174:177], v[102:105]
	v_mfma_f32_16x16x32_bf16 v[98:101], v[158:161], v[174:177], v[98:101]
	v_mfma_f32_16x16x32_bf16 v[86:89], v[142:145], v[182:185], v[86:89]
	v_mfma_f32_16x16x32_bf16 v[82:85], v[158:161], v[182:185], v[82:85]
	v_mfma_f32_16x16x32_bf16 v[70:73], v[142:145], v[190:193], v[70:73]
	v_mfma_f32_16x16x32_bf16 v[66:69], v[158:161], v[190:193], v[66:69]
	s_barrier
	s_add_i32 s18, s42, s16
	v_lshl_add_u64 v[210:211], s[26:27], 0, v[196:197]
	s_mov_b32 m0, s18
	ds_read_b128 v[162:165], v249 offset:16384
	ds_read_b128 v[166:169], v249 offset:17408
	ds_read_b128 v[170:173], v249 offset:18432
	ds_read_b128 v[174:177], v249 offset:19456
	ds_read_b128 v[178:181], v249 offset:20480
	ds_read_b128 v[182:185], v249 offset:21504
	ds_read_b128 v[186:189], v249 offset:22528
	ds_read_b128 v[190:193], v249 offset:23552
	global_load_lds_dwordx4 v[210:211], off
	s_add_i32 m0, s18, 0x2000
	s_add_u32 s18, s26, 0x380000
	v_lshl_add_u64 v[212:213], s[26:27], 0, v[200:201]
	s_addc_u32 s19, s27, 0
	s_add_i32 s67, s43, s16
	global_load_lds_dwordx4 v[212:213], off
	v_lshl_add_u64 v[214:215], s[18:19], 0, v[196:197]
	s_mov_b32 m0, s67
	v_lshl_add_u64 v[216:217], s[28:29], 0, v[198:199]
	global_load_lds_dwordx4 v[214:215], off
	v_lshl_add_u64 v[214:215], s[18:19], 0, v[200:201]
	s_add_i32 m0, s67, 0x2000
	s_nop 0
	global_load_lds_dwordx4 v[214:215], off
	v_lshl_add_u64 v[214:215], s[28:29], 0, v[194:195]
	s_mov_b32 m0, s17
	s_nop 0
	global_load_lds_dwordx4 v[214:215], off
	s_mov_b32 m0, s30
	s_nop 0
	global_load_lds_dwordx4 v[216:217], off
	s_waitcnt vmcnt(8)
	s_waitcnt lgkmcnt(0)
	s_barrier
	v_mfma_f32_16x16x32_bf16 v[62:65], v[114:117], v[162:165], 0
	v_mfma_f32_16x16x32_bf16 v[58:61], v[126:129], v[162:165], 0
	v_mfma_f32_16x16x32_bf16 v[46:49], v[114:117], v[170:173], 0
	v_mfma_f32_16x16x32_bf16 v[42:45], v[126:129], v[170:173], 0
	v_mfma_f32_16x16x32_bf16 v[30:33], v[114:117], v[178:181], 0
	v_mfma_f32_16x16x32_bf16 v[26:29], v[126:129], v[178:181], 0
	v_mfma_f32_16x16x32_bf16 v[14:17], v[114:117], v[186:189], 0
	v_mfma_f32_16x16x32_bf16 v[10:13], v[126:129], v[186:189], 0
	v_mfma_f32_16x16x32_bf16 v[62:65], v[118:121], v[166:169], v[62:65]
	v_mfma_f32_16x16x32_bf16 v[58:61], v[134:137], v[166:169], v[58:61]
	v_mfma_f32_16x16x32_bf16 v[46:49], v[118:121], v[174:177], v[46:49]
	v_mfma_f32_16x16x32_bf16 v[42:45], v[134:137], v[174:177], v[42:45]
	v_mfma_f32_16x16x32_bf16 v[30:33], v[118:121], v[182:185], v[30:33]
	v_mfma_f32_16x16x32_bf16 v[26:29], v[134:137], v[182:185], v[26:29]
	v_mfma_f32_16x16x32_bf16 v[14:17], v[118:121], v[190:193], v[14:17]
	v_mfma_f32_16x16x32_bf16 v[10:13], v[134:137], v[190:193], v[10:13]
	v_mfma_f32_16x16x32_bf16 v[54:57], v[138:141], v[162:165], 0
	v_mfma_f32_16x16x32_bf16 v[50:53], v[154:157], v[162:165], 0
	v_mfma_f32_16x16x32_bf16 v[38:41], v[138:141], v[170:173], 0
	v_mfma_f32_16x16x32_bf16 v[34:37], v[154:157], v[170:173], 0
	v_mfma_f32_16x16x32_bf16 v[22:25], v[138:141], v[178:181], 0
	v_mfma_f32_16x16x32_bf16 v[18:21], v[154:157], v[178:181], 0
	v_mfma_f32_16x16x32_bf16 v[6:9], v[138:141], v[186:189], 0
	v_mfma_f32_16x16x32_bf16 v[2:5], v[154:157], v[186:189], 0
	v_mfma_f32_16x16x32_bf16 v[54:57], v[142:145], v[166:169], v[54:57]
	v_mfma_f32_16x16x32_bf16 v[50:53], v[158:161], v[166:169], v[50:53]
	v_mfma_f32_16x16x32_bf16 v[38:41], v[142:145], v[174:177], v[38:41]
	v_mfma_f32_16x16x32_bf16 v[34:37], v[158:161], v[174:177], v[34:37]
	v_mfma_f32_16x16x32_bf16 v[22:25], v[142:145], v[182:185], v[22:25]
	v_mfma_f32_16x16x32_bf16 v[18:21], v[158:161], v[182:185], v[18:21]
	v_mfma_f32_16x16x32_bf16 v[6:9], v[142:145], v[190:193], v[6:9]
	v_mfma_f32_16x16x32_bf16 v[2:5], v[158:161], v[190:193], v[2:5]
	s_barrier
	s_add_i32 s67, 0, 0x18000
	s_add_i32 s68, 0, 0x1c000
	v_add_u32_e32 v134, s67, v244
	v_add_u32_e32 v158, s68, v244
	ds_read_b128 v[114:117], v134
	ds_read_b128 v[118:121], v134 offset:1024
	ds_read_b128 v[126:129], v134 offset:2048
	ds_read_b128 v[134:137], v134 offset:3072
	ds_read_b128 v[138:141], v158
	ds_read_b128 v[142:145], v158 offset:1024
	ds_read_b128 v[154:157], v158 offset:2048
	ds_read_b128 v[158:161], v158 offset:3072
	s_add_u32 s18, s28, 0x380000
	s_addc_u32 s19, s29, 0
	s_mov_b32 m0, s31
	v_lshl_add_u64 v[218:219], s[18:19], 0, v[194:195]
	ds_read_b128 v[162:165], v249 offset:32768
	ds_read_b128 v[166:169], v249 offset:33792
	ds_read_b128 v[170:173], v249 offset:34816
	ds_read_b128 v[174:177], v249 offset:35840
	ds_read_b128 v[178:181], v249 offset:36864
	ds_read_b128 v[182:185], v249 offset:37888
	ds_read_b128 v[186:189], v249 offset:38912
	ds_read_b128 v[190:193], v249 offset:39936
	global_load_lds_dwordx4 v[218:219], off
	v_lshl_add_u64 v[218:219], s[18:19], 0, v[198:199]
	s_mov_b32 m0, s34
	s_nop 0
	global_load_lds_dwordx4 v[218:219], off
	s_waitcnt vmcnt(8)
	s_waitcnt lgkmcnt(0)
	s_barrier
	v_mfma_f32_16x16x32_bf16 v[150:153], v[114:117], v[162:165], v[150:153]
	v_mfma_f32_16x16x32_bf16 v[146:149], v[126:129], v[162:165], v[146:149]
	v_mfma_f32_16x16x32_bf16 v[110:113], v[114:117], v[170:173], v[110:113]
	v_mfma_f32_16x16x32_bf16 v[106:109], v[126:129], v[170:173], v[106:109]
	v_mfma_f32_16x16x32_bf16 v[94:97], v[114:117], v[178:181], v[94:97]
	v_mfma_f32_16x16x32_bf16 v[90:93], v[126:129], v[178:181], v[90:93]
	v_mfma_f32_16x16x32_bf16 v[78:81], v[114:117], v[186:189], v[78:81]
	v_mfma_f32_16x16x32_bf16 v[74:77], v[126:129], v[186:189], v[74:77]
	v_mfma_f32_16x16x32_bf16 v[150:153], v[118:121], v[166:169], v[150:153]
	v_mfma_f32_16x16x32_bf16 v[146:149], v[134:137], v[166:169], v[146:149]
	v_mfma_f32_16x16x32_bf16 v[110:113], v[118:121], v[174:177], v[110:113]
	v_mfma_f32_16x16x32_bf16 v[106:109], v[134:137], v[174:177], v[106:109]
	v_mfma_f32_16x16x32_bf16 v[94:97], v[118:121], v[182:185], v[94:97]
	v_mfma_f32_16x16x32_bf16 v[90:93], v[134:137], v[182:185], v[90:93]
	v_mfma_f32_16x16x32_bf16 v[78:81], v[118:121], v[190:193], v[78:81]
	v_mfma_f32_16x16x32_bf16 v[74:77], v[134:137], v[190:193], v[74:77]
	v_mfma_f32_16x16x32_bf16 v[130:133], v[138:141], v[162:165], v[130:133]
	v_mfma_f32_16x16x32_bf16 v[122:125], v[154:157], v[162:165], v[122:125]
	v_mfma_f32_16x16x32_bf16 v[102:105], v[138:141], v[170:173], v[102:105]
	v_mfma_f32_16x16x32_bf16 v[98:101], v[154:157], v[170:173], v[98:101]
	v_mfma_f32_16x16x32_bf16 v[86:89], v[138:141], v[178:181], v[86:89]
	v_mfma_f32_16x16x32_bf16 v[82:85], v[154:157], v[178:181], v[82:85]
	v_mfma_f32_16x16x32_bf16 v[70:73], v[138:141], v[186:189], v[70:73]
	v_mfma_f32_16x16x32_bf16 v[66:69], v[154:157], v[186:189], v[66:69]
	v_mfma_f32_16x16x32_bf16 v[130:133], v[142:145], v[166:169], v[130:133]
	v_mfma_f32_16x16x32_bf16 v[122:125], v[158:161], v[166:169], v[122:125]
	v_mfma_f32_16x16x32_bf16 v[102:105], v[142:145], v[174:177], v[102:105]
	v_mfma_f32_16x16x32_bf16 v[98:101], v[158:161], v[174:177], v[98:101]
	v_mfma_f32_16x16x32_bf16 v[86:89], v[142:145], v[182:185], v[86:89]
	v_mfma_f32_16x16x32_bf16 v[82:85], v[158:161], v[182:185], v[82:85]
	v_mfma_f32_16x16x32_bf16 v[70:73], v[142:145], v[190:193], v[70:73]
	v_mfma_f32_16x16x32_bf16 v[66:69], v[158:161], v[190:193], v[66:69]
	s_barrier
	s_add_i32 s18, s67, s16
	v_lshl_add_u64 v[210:211], v[210:211], 0, s[12:13]
	s_mov_b32 m0, s18
	ds_read_b128 v[162:165], v249 offset:49152
	ds_read_b128 v[166:169], v249 offset:50176
	ds_read_b128 v[170:173], v249 offset:51200
	ds_read_b128 v[174:177], v249 offset:52224
	ds_read_b128 v[178:181], v249 offset:53248
	ds_read_b128 v[182:185], v249 offset:54272
	ds_read_b128 v[186:189], v249 offset:55296
	ds_read_b128 v[190:193], v249 offset:56320
	global_load_lds_dwordx4 v[210:211], off
	s_add_i32 m0, s18, 0x2000
	s_add_u32 s18, s26, 0x380080
	v_lshl_add_u64 v[210:211], v[212:213], 0, s[12:13]
	s_addc_u32 s19, s27, 0
	s_add_i32 s26, s68, s16
	global_load_lds_dwordx4 v[210:211], off
	v_lshl_add_u64 v[210:211], s[18:19], 0, v[196:197]
	s_mov_b32 m0, s26
	s_nop 0
	global_load_lds_dwordx4 v[210:211], off
	v_lshl_add_u64 v[210:211], s[18:19], 0, v[200:201]
	s_add_i32 m0, s26, 0x2000
	s_nop 0
	global_load_lds_dwordx4 v[210:211], off
	v_lshl_add_u64 v[210:211], v[214:215], 0, s[12:13]
	s_mov_b32 m0, s38
	s_nop 0
	global_load_lds_dwordx4 v[210:211], off
	v_lshl_add_u64 v[210:211], v[216:217], 0, s[12:13]
	s_mov_b32 m0, s39
	s_nop 0
	global_load_lds_dwordx4 v[210:211], off
	s_waitcnt vmcnt(8)
	s_waitcnt lgkmcnt(0)
	s_barrier
	v_mfma_f32_16x16x32_bf16 v[62:65], v[114:117], v[162:165], v[62:65]
	v_mfma_f32_16x16x32_bf16 v[58:61], v[126:129], v[162:165], v[58:61]
	v_mfma_f32_16x16x32_bf16 v[46:49], v[114:117], v[170:173], v[46:49]
	v_mfma_f32_16x16x32_bf16 v[42:45], v[126:129], v[170:173], v[42:45]
	v_mfma_f32_16x16x32_bf16 v[30:33], v[114:117], v[178:181], v[30:33]
	v_mfma_f32_16x16x32_bf16 v[26:29], v[126:129], v[178:181], v[26:29]
	v_mfma_f32_16x16x32_bf16 v[14:17], v[114:117], v[186:189], v[14:17]
	v_mfma_f32_16x16x32_bf16 v[10:13], v[126:129], v[186:189], v[10:13]
	v_mfma_f32_16x16x32_bf16 v[62:65], v[118:121], v[166:169], v[62:65]
	v_mfma_f32_16x16x32_bf16 v[58:61], v[134:137], v[166:169], v[58:61]
	v_mfma_f32_16x16x32_bf16 v[46:49], v[118:121], v[174:177], v[46:49]
	v_mfma_f32_16x16x32_bf16 v[42:45], v[134:137], v[174:177], v[42:45]
	v_mfma_f32_16x16x32_bf16 v[30:33], v[118:121], v[182:185], v[30:33]
	v_mfma_f32_16x16x32_bf16 v[26:29], v[134:137], v[182:185], v[26:29]
	v_mfma_f32_16x16x32_bf16 v[14:17], v[118:121], v[190:193], v[14:17]
	v_mfma_f32_16x16x32_bf16 v[10:13], v[134:137], v[190:193], v[10:13]
	v_mfma_f32_16x16x32_bf16 v[54:57], v[138:141], v[162:165], v[54:57]
	v_mfma_f32_16x16x32_bf16 v[50:53], v[154:157], v[162:165], v[50:53]
	v_mfma_f32_16x16x32_bf16 v[38:41], v[138:141], v[170:173], v[38:41]
	v_mfma_f32_16x16x32_bf16 v[34:37], v[154:157], v[170:173], v[34:37]
	v_mfma_f32_16x16x32_bf16 v[22:25], v[138:141], v[178:181], v[22:25]
	v_mfma_f32_16x16x32_bf16 v[18:21], v[154:157], v[178:181], v[18:21]
	v_mfma_f32_16x16x32_bf16 v[6:9], v[138:141], v[186:189], v[6:9]
	v_mfma_f32_16x16x32_bf16 v[2:5], v[154:157], v[186:189], v[2:5]
	v_mfma_f32_16x16x32_bf16 v[54:57], v[142:145], v[166:169], v[54:57]
	v_mfma_f32_16x16x32_bf16 v[50:53], v[158:161], v[166:169], v[50:53]
	v_mfma_f32_16x16x32_bf16 v[38:41], v[142:145], v[174:177], v[38:41]
	v_mfma_f32_16x16x32_bf16 v[34:37], v[158:161], v[174:177], v[34:37]
	v_mfma_f32_16x16x32_bf16 v[22:25], v[142:145], v[182:185], v[22:25]
	v_mfma_f32_16x16x32_bf16 v[18:21], v[158:161], v[182:185], v[18:21]
	v_mfma_f32_16x16x32_bf16 v[6:9], v[142:145], v[190:193], v[6:9]
	v_mfma_f32_16x16x32_bf16 v[2:5], v[158:161], v[190:193], v[2:5]
	s_barrier
	s_add_i32 s66, s66, 2
	s_add_u32 s64, s64, 0x100
	s_addc_u32 s65, s65, 0
	s_cmpk_gt_u32 s66, 0xdd
	s_mov_b64 s[18:19], s[4:5]

.LBB0_1646:
	s_ashr_i32 s63, s62, 31
	s_lshl_b64 s[0:1], s[62:63], 21
	s_add_u32 s64, s52, s0
	s_addc_u32 s65, s53, s1
	s_and_b64 s[0:1], s[4:5], exec
	s_cselect_b32 s0, s65, s11
	s_cselect_b32 s1, s64, s10
	s_ashr_i32 s61, s60, 31
	s_lshl_b64 s[16:17], s[60:61], 21
	s_add_u32 s66, s31, s16
	s_addc_u32 s67, s35, s17
	s_and_b64 s[16:17], s[4:5], exec
	s_cselect_b32 s7, s67, s19
	s_cselect_b32 s9, s66, s18
	s_add_u32 s10, s10, 0x100080
	s_addc_u32 s11, s11, 0
	s_add_u32 s16, s18, 0x100
	s_addc_u32 s17, s19, 0
	s_mov_b32 s61, -2
	s_waitcnt lgkmcnt(0)
	ds_read_b128 v[30:33], v200
	ds_read_b128 v[38:41], v200 offset:1024
	ds_read_b128 v[42:45], v200 offset:2048
	ds_read_b128 v[50:53], v200 offset:3072
	ds_read_b128 v[164:167], v201
	ds_read_b128 v[168:171], v201 offset:1024
	ds_read_b128 v[172:175], v201 offset:2048
	ds_read_b128 v[176:179], v201 offset:3072
	s_add_u32 s18, s10, 0xfff00080
	s_addc_u32 s19, s11, -1
	s_cmp_eq_u32 s61, 60
	s_cselect_b32 s69, s0, s19
	s_cselect_b32 s68, s1, s18
	s_cselect_b32 s19, s7, s17
	s_cselect_b32 s18, s9, s16
	v_lshl_add_u64 v[222:223], s[10:11], 0, v[156:157]
	s_add_i32 m0, s39, 0xc000
	ds_read_b128 v[180:183], v202
	ds_read_b128 v[184:187], v202 offset:1024
	ds_read_b128 v[188:191], v202 offset:2048
	ds_read_b128 v[192:195], v202 offset:3072
	ds_read_b128 v[206:209], v202 offset:4096
	ds_read_b128 v[210:213], v202 offset:5120
	ds_read_b128 v[214:217], v202 offset:6144
	ds_read_b128 v[218:221], v202 offset:7168
	global_load_lds_dwordx4 v[222:223], off
	v_lshl_add_u64 v[222:223], s[10:11], 0, v[158:159]
	s_add_i32 m0, s39, 0xe000
	s_nop 0
	global_load_lds_dwordx4 v[222:223], off
	s_waitcnt vmcnt(8)
	s_waitcnt lgkmcnt(0)
	s_barrier
	v_mfma_f32_16x16x32_bf16 v[138:141], v[30:33], v[180:183], 0
	v_mfma_f32_16x16x32_bf16 v[142:145], v[42:45], v[180:183], 0
	v_mfma_f32_16x16x32_bf16 v[122:125], v[30:33], v[188:191], 0
	v_mfma_f32_16x16x32_bf16 v[126:129], v[42:45], v[188:191], 0
	v_mfma_f32_16x16x32_bf16 v[106:109], v[30:33], v[206:209], 0
	v_mfma_f32_16x16x32_bf16 v[110:113], v[42:45], v[206:209], 0
	v_mfma_f32_16x16x32_bf16 v[90:93], v[30:33], v[214:217], 0
	v_mfma_f32_16x16x32_bf16 v[94:97], v[42:45], v[214:217], 0
	v_mfma_f32_16x16x32_bf16 v[138:141], v[38:41], v[184:187], v[138:141]
	v_mfma_f32_16x16x32_bf16 v[142:145], v[50:53], v[184:187], v[142:145]
	v_mfma_f32_16x16x32_bf16 v[122:125], v[38:41], v[192:195], v[122:125]
	v_mfma_f32_16x16x32_bf16 v[126:129], v[50:53], v[192:195], v[126:129]
	v_mfma_f32_16x16x32_bf16 v[106:109], v[38:41], v[210:213], v[106:109]
	v_mfma_f32_16x16x32_bf16 v[110:113], v[50:53], v[210:213], v[110:113]
	v_mfma_f32_16x16x32_bf16 v[90:93], v[38:41], v[218:221], v[90:93]
	v_mfma_f32_16x16x32_bf16 v[94:97], v[50:53], v[218:221], v[94:97]
	v_mfma_f32_16x16x32_bf16 v[130:133], v[164:167], v[180:183], 0
	v_mfma_f32_16x16x32_bf16 v[134:137], v[172:175], v[180:183], 0
	v_mfma_f32_16x16x32_bf16 v[114:117], v[164:167], v[188:191], 0
	v_mfma_f32_16x16x32_bf16 v[118:121], v[172:175], v[188:191], 0
	v_mfma_f32_16x16x32_bf16 v[98:101], v[164:167], v[206:209], 0
	v_mfma_f32_16x16x32_bf16 v[102:105], v[172:175], v[206:209], 0
	v_mfma_f32_16x16x32_bf16 v[82:85], v[164:167], v[214:217], 0
	v_mfma_f32_16x16x32_bf16 v[86:89], v[172:175], v[214:217], 0
	v_mfma_f32_16x16x32_bf16 v[130:133], v[168:171], v[184:187], v[130:133]
	v_mfma_f32_16x16x32_bf16 v[134:137], v[176:179], v[184:187], v[134:137]
	v_mfma_f32_16x16x32_bf16 v[114:117], v[168:171], v[192:195], v[114:117]
	v_mfma_f32_16x16x32_bf16 v[118:121], v[176:179], v[192:195], v[118:121]
	v_mfma_f32_16x16x32_bf16 v[98:101], v[168:171], v[210:213], v[98:101]
	v_mfma_f32_16x16x32_bf16 v[102:105], v[176:179], v[210:213], v[102:105]
	v_mfma_f32_16x16x32_bf16 v[82:85], v[168:171], v[218:221], v[82:85]
	v_mfma_f32_16x16x32_bf16 v[86:89], v[176:179], v[218:221], v[86:89]
	s_barrier
	s_add_i32 s63, s77, s37
	v_lshl_add_u64 v[222:223], s[18:19], 0, v[148:149]
	s_mov_b32 m0, s63
	ds_read_b128 v[180:183], v202 offset:16384
	ds_read_b128 v[184:187], v202 offset:17408
	ds_read_b128 v[188:191], v202 offset:18432
	ds_read_b128 v[192:195], v202 offset:19456
	ds_read_b128 v[206:209], v202 offset:20480
	ds_read_b128 v[210:213], v202 offset:21504
	ds_read_b128 v[214:217], v202 offset:22528
	ds_read_b128 v[218:221], v202 offset:23552
	global_load_lds_dwordx4 v[222:223], off
	s_add_i32 m0, s63, 0x2000
	s_add_u32 s82, s18, 0x100000
	v_lshl_add_u64 v[224:225], s[18:19], 0, v[152:153]
	s_addc_u32 s83, s19, 0
	s_add_i32 s63, s78, s37
	global_load_lds_dwordx4 v[224:225], off
	v_lshl_add_u64 v[226:227], s[82:83], 0, v[148:149]
	s_mov_b32 m0, s63
	v_lshl_add_u64 v[228:229], s[68:69], 0, v[150:151]
	global_load_lds_dwordx4 v[226:227], off
	v_lshl_add_u64 v[226:227], s[82:83], 0, v[152:153]
	s_add_i32 m0, s63, 0x2000
	s_nop 0
	global_load_lds_dwordx4 v[226:227], off
	v_lshl_add_u64 v[226:227], s[68:69], 0, v[146:147]
	s_mov_b32 m0, s39
	s_nop 0
	global_load_lds_dwordx4 v[226:227], off
	s_mov_b32 m0, s41
	s_nop 0
	global_load_lds_dwordx4 v[228:229], off
	s_waitcnt vmcnt(8)
	s_waitcnt lgkmcnt(0)
	s_barrier
	v_mfma_f32_16x16x32_bf16 v[74:77], v[30:33], v[180:183], 0
	v_mfma_f32_16x16x32_bf16 v[78:81], v[42:45], v[180:183], 0
	v_mfma_f32_16x16x32_bf16 v[58:61], v[30:33], v[188:191], 0
	v_mfma_f32_16x16x32_bf16 v[62:65], v[42:45], v[188:191], 0
	v_mfma_f32_16x16x32_bf16 v[26:29], v[30:33], v[206:209], 0
	v_mfma_f32_16x16x32_bf16 v[34:37], v[42:45], v[206:209], 0
	v_mfma_f32_16x16x32_bf16 v[10:13], v[30:33], v[214:217], 0
	v_mfma_f32_16x16x32_bf16 v[14:17], v[42:45], v[214:217], 0
	v_mfma_f32_16x16x32_bf16 v[74:77], v[38:41], v[184:187], v[74:77]
	v_mfma_f32_16x16x32_bf16 v[78:81], v[50:53], v[184:187], v[78:81]
	v_mfma_f32_16x16x32_bf16 v[58:61], v[38:41], v[192:195], v[58:61]
	v_mfma_f32_16x16x32_bf16 v[62:65], v[50:53], v[192:195], v[62:65]
	v_mfma_f32_16x16x32_bf16 v[26:29], v[38:41], v[210:213], v[26:29]
	v_mfma_f32_16x16x32_bf16 v[34:37], v[50:53], v[210:213], v[34:37]
	v_mfma_f32_16x16x32_bf16 v[10:13], v[38:41], v[218:221], v[10:13]
	v_mfma_f32_16x16x32_bf16 v[14:17], v[50:53], v[218:221], v[14:17]
	v_mfma_f32_16x16x32_bf16 v[18:21], v[164:167], v[206:209], 0
	v_mfma_f32_16x16x32_bf16 v[22:25], v[172:175], v[206:209], 0
	v_mfma_f32_16x16x32_bf16 v[2:5], v[164:167], v[214:217], 0
	v_mfma_f32_16x16x32_bf16 v[6:9], v[172:175], v[214:217], 0
	v_mfma_f32_16x16x32_bf16 v[30:33], v[164:167], v[180:183], 0
	v_mfma_f32_16x16x32_bf16 v[38:41], v[172:175], v[180:183], 0
	v_mfma_f32_16x16x32_bf16 v[42:45], v[164:167], v[188:191], 0
	v_mfma_f32_16x16x32_bf16 v[46:49], v[172:175], v[188:191], 0
	v_mfma_f32_16x16x32_bf16 v[18:21], v[168:171], v[210:213], v[18:21]
	v_mfma_f32_16x16x32_bf16 v[22:25], v[176:179], v[210:213], v[22:25]
	v_mfma_f32_16x16x32_bf16 v[2:5], v[168:171], v[218:221], v[2:5]
	v_mfma_f32_16x16x32_bf16 v[6:9], v[176:179], v[218:221], v[6:9]
	v_mfma_f32_16x16x32_bf16 v[30:33], v[168:171], v[184:187], v[30:33]
	v_mfma_f32_16x16x32_bf16 v[38:41], v[176:179], v[184:187], v[38:41]
	v_mfma_f32_16x16x32_bf16 v[42:45], v[168:171], v[192:195], v[42:45]
	v_mfma_f32_16x16x32_bf16 v[50:53], v[176:179], v[192:195], v[46:49]
	s_barrier
	s_add_i32 s63, 0, 0x18000
	s_add_i32 s82, 0, 0x1c000
	v_add_u32_e32 v70, s63, v196
	v_add_u32_e32 v155, s82, v196
	ds_read_b128 v[46:49], v70
	ds_read_b128 v[54:57], v70 offset:1024
	ds_read_b128 v[66:69], v70 offset:2048
	ds_read_b128 v[70:73], v70 offset:3072
	ds_read_b128 v[164:167], v155
	ds_read_b128 v[168:171], v155 offset:1024
	ds_read_b128 v[172:175], v155 offset:2048
	ds_read_b128 v[176:179], v155 offset:3072
	s_add_u32 s68, s68, 0x100000
	s_addc_u32 s69, s69, 0
	s_mov_b32 m0, s43
	v_lshl_add_u64 v[230:231], s[68:69], 0, v[146:147]
	ds_read_b128 v[180:183], v202 offset:32768
	ds_read_b128 v[184:187], v202 offset:33792
	ds_read_b128 v[188:191], v202 offset:34816
	ds_read_b128 v[192:195], v202 offset:35840
	ds_read_b128 v[206:209], v202 offset:36864
	ds_read_b128 v[210:213], v202 offset:37888
	ds_read_b128 v[214:217], v202 offset:38912
	ds_read_b128 v[218:221], v202 offset:39936
	global_load_lds_dwordx4 v[230:231], off
	v_lshl_add_u64 v[230:231], s[68:69], 0, v[150:151]
	s_mov_b32 m0, s57
	s_nop 0
	global_load_lds_dwordx4 v[230:231], off
	s_waitcnt vmcnt(8)
	s_waitcnt lgkmcnt(0)
	s_barrier
	v_mfma_f32_16x16x32_bf16 v[138:141], v[46:49], v[180:183], v[138:141]
	v_mfma_f32_16x16x32_bf16 v[142:145], v[66:69], v[180:183], v[142:145]
	v_mfma_f32_16x16x32_bf16 v[122:125], v[46:49], v[188:191], v[122:125]
	v_mfma_f32_16x16x32_bf16 v[126:129], v[66:69], v[188:191], v[126:129]
	v_mfma_f32_16x16x32_bf16 v[106:109], v[46:49], v[206:209], v[106:109]
	v_mfma_f32_16x16x32_bf16 v[110:113], v[66:69], v[206:209], v[110:113]
	v_mfma_f32_16x16x32_bf16 v[90:93], v[46:49], v[214:217], v[90:93]
	v_mfma_f32_16x16x32_bf16 v[94:97], v[66:69], v[214:217], v[94:97]
	v_mfma_f32_16x16x32_bf16 v[138:141], v[54:57], v[184:187], v[138:141]
	v_mfma_f32_16x16x32_bf16 v[142:145], v[70:73], v[184:187], v[142:145]
	v_mfma_f32_16x16x32_bf16 v[122:125], v[54:57], v[192:195], v[122:125]
	v_mfma_f32_16x16x32_bf16 v[126:129], v[70:73], v[192:195], v[126:129]
	v_mfma_f32_16x16x32_bf16 v[106:109], v[54:57], v[210:213], v[106:109]
	v_mfma_f32_16x16x32_bf16 v[110:113], v[70:73], v[210:213], v[110:113]
	v_mfma_f32_16x16x32_bf16 v[90:93], v[54:57], v[218:221], v[90:93]
	v_mfma_f32_16x16x32_bf16 v[94:97], v[70:73], v[218:221], v[94:97]
	v_mfma_f32_16x16x32_bf16 v[130:133], v[164:167], v[180:183], v[130:133]
	v_mfma_f32_16x16x32_bf16 v[134:137], v[172:175], v[180:183], v[134:137]
	v_mfma_f32_16x16x32_bf16 v[114:117], v[164:167], v[188:191], v[114:117]
	v_mfma_f32_16x16x32_bf16 v[118:121], v[172:175], v[188:191], v[118:121]
	v_mfma_f32_16x16x32_bf16 v[98:101], v[164:167], v[206:209], v[98:101]
	v_mfma_f32_16x16x32_bf16 v[102:105], v[172:175], v[206:209], v[102:105]
	v_mfma_f32_16x16x32_bf16 v[82:85], v[164:167], v[214:217], v[82:85]
	v_mfma_f32_16x16x32_bf16 v[86:89], v[172:175], v[214:217], v[86:89]
	v_mfma_f32_16x16x32_bf16 v[130:133], v[168:171], v[184:187], v[130:133]
	v_mfma_f32_16x16x32_bf16 v[134:137], v[176:179], v[184:187], v[134:137]
	v_mfma_f32_16x16x32_bf16 v[114:117], v[168:171], v[192:195], v[114:117]
	v_mfma_f32_16x16x32_bf16 v[118:121], v[176:179], v[192:195], v[118:121]
	v_mfma_f32_16x16x32_bf16 v[98:101], v[168:171], v[210:213], v[98:101]
	v_mfma_f32_16x16x32_bf16 v[102:105], v[176:179], v[210:213], v[102:105]
	v_mfma_f32_16x16x32_bf16 v[82:85], v[168:171], v[218:221], v[82:85]
	v_mfma_f32_16x16x32_bf16 v[86:89], v[176:179], v[218:221], v[86:89]
	s_barrier
	s_add_i32 s63, s63, s37
	v_lshl_add_u64 v[222:223], v[222:223], 0, s[26:27]
	s_mov_b32 m0, s63
	ds_read_b128 v[180:183], v202 offset:49152
	ds_read_b128 v[184:187], v202 offset:50176
	ds_read_b128 v[188:191], v202 offset:51200
	ds_read_b128 v[192:195], v202 offset:52224
	ds_read_b128 v[206:209], v202 offset:53248
	ds_read_b128 v[210:213], v202 offset:54272
	ds_read_b128 v[214:217], v202 offset:55296
	ds_read_b128 v[218:221], v202 offset:56320
	global_load_lds_dwordx4 v[222:223], off
	s_add_i32 m0, s63, 0x2000
	s_add_u32 s18, s18, 0x100080
	v_lshl_add_u64 v[222:223], v[224:225], 0, s[26:27]
	s_addc_u32 s19, s19, 0
	s_add_i32 s63, s82, s37
	global_load_lds_dwordx4 v[222:223], off
	v_lshl_add_u64 v[222:223], s[18:19], 0, v[148:149]
	s_mov_b32 m0, s63
	s_nop 0
	global_load_lds_dwordx4 v[222:223], off
	v_lshl_add_u64 v[222:223], s[18:19], 0, v[152:153]
	s_add_i32 m0, s63, 0x2000
	s_nop 0
	global_load_lds_dwordx4 v[222:223], off
	v_lshl_add_u64 v[222:223], v[226:227], 0, s[26:27]
	s_mov_b32 m0, s71
	s_nop 0
	global_load_lds_dwordx4 v[222:223], off
	v_lshl_add_u64 v[222:223], v[228:229], 0, s[26:27]
	s_mov_b32 m0, s72
	s_nop 0
	global_load_lds_dwordx4 v[222:223], off
	s_waitcnt vmcnt(8)
	s_waitcnt lgkmcnt(0)
	s_barrier
	v_mfma_f32_16x16x32_bf16 v[74:77], v[46:49], v[180:183], v[74:77]
	v_mfma_f32_16x16x32_bf16 v[78:81], v[66:69], v[180:183], v[78:81]
	v_mfma_f32_16x16x32_bf16 v[58:61], v[46:49], v[188:191], v[58:61]
	v_mfma_f32_16x16x32_bf16 v[62:65], v[66:69], v[188:191], v[62:65]
	v_mfma_f32_16x16x32_bf16 v[26:29], v[46:49], v[206:209], v[26:29]
	v_mfma_f32_16x16x32_bf16 v[34:37], v[66:69], v[206:209], v[34:37]
	v_mfma_f32_16x16x32_bf16 v[10:13], v[46:49], v[214:217], v[10:13]
	v_mfma_f32_16x16x32_bf16 v[14:17], v[66:69], v[214:217], v[14:17]
	v_mfma_f32_16x16x32_bf16 v[74:77], v[54:57], v[184:187], v[74:77]
	v_mfma_f32_16x16x32_bf16 v[78:81], v[70:73], v[184:187], v[78:81]
	v_mfma_f32_16x16x32_bf16 v[58:61], v[54:57], v[192:195], v[58:61]
	v_mfma_f32_16x16x32_bf16 v[62:65], v[70:73], v[192:195], v[62:65]
	v_mfma_f32_16x16x32_bf16 v[26:29], v[54:57], v[210:213], v[26:29]
	v_mfma_f32_16x16x32_bf16 v[34:37], v[70:73], v[210:213], v[34:37]
	v_mfma_f32_16x16x32_bf16 v[10:13], v[54:57], v[218:221], v[10:13]
	v_mfma_f32_16x16x32_bf16 v[14:17], v[70:73], v[218:221], v[14:17]
	v_mfma_f32_16x16x32_bf16 v[30:33], v[164:167], v[180:183], v[30:33]
	v_mfma_f32_16x16x32_bf16 v[66:69], v[168:171], v[184:187], v[30:33]
	v_mfma_f32_16x16x32_bf16 v[30:33], v[172:175], v[180:183], v[38:41]
	v_mfma_f32_16x16x32_bf16 v[70:73], v[176:179], v[184:187], v[30:33]
	v_mfma_f32_16x16x32_bf16 v[30:33], v[164:167], v[188:191], v[42:45]
	v_mfma_f32_16x16x32_bf16 v[46:49], v[168:171], v[192:195], v[30:33]
	v_mfma_f32_16x16x32_bf16 v[30:33], v[172:175], v[188:191], v[50:53]
	v_mfma_f32_16x16x32_bf16 v[18:21], v[164:167], v[206:209], v[18:21]
	v_mfma_f32_16x16x32_bf16 v[22:25], v[172:175], v[206:209], v[22:25]
	v_mfma_f32_16x16x32_bf16 v[2:5], v[164:167], v[214:217], v[2:5]
	v_mfma_f32_16x16x32_bf16 v[6:9], v[172:175], v[214:217], v[6:9]
	v_mfma_f32_16x16x32_bf16 v[54:57], v[176:179], v[192:195], v[30:33]
	v_mfma_f32_16x16x32_bf16 v[18:21], v[168:171], v[210:213], v[18:21]
	v_mfma_f32_16x16x32_bf16 v[22:25], v[176:179], v[210:213], v[22:25]
	v_mfma_f32_16x16x32_bf16 v[2:5], v[168:171], v[218:221], v[2:5]
	v_mfma_f32_16x16x32_bf16 v[6:9], v[176:179], v[218:221], v[6:9]
	s_barrier
	s_add_i32 s61, s61, 2
	s_add_u32 s10, s10, 0x100
	s_addc_u32 s11, s11, 0
	s_add_u32 s16, s16, 0x100
	s_addc_u32 s17, s17, 0
	s_cmp_gt_u32 s61, 61

.LBB0_1920:
	s_ashr_i32 s31, s30, 31
	s_lshl_b64 s[34:35], s[30:31], 21
	s_add_u32 s34, s54, s34
	s_addc_u32 s35, s55, s35
	s_and_b64 s[36:37], s[2:3], exec
	s_cselect_b32 s31, s35, s39
	s_cselect_b32 s69, s34, s38
	s_ashr_i32 s29, s28, 31
	s_lshl_b64 s[36:37], s[28:29], 21
	s_add_u32 s36, s1, s36
	s_addc_u32 s37, s16, s37
	s_and_b64 s[42:43], s[2:3], exec
	s_cselect_b32 s29, s37, s41
	s_cselect_b32 s70, s36, s40
	s_add_u32 s38, s38, 0x100080
	s_addc_u32 s39, s39, 0
	s_add_u32 s71, s40, 0x100
	s_addc_u32 s72, s41, 0
	s_mov_b32 s73, -2
	ds_read_b128 v[130:133], v212
	ds_read_b128 v[134:137], v212 offset:1024
	ds_read_b128 v[138:141], v212 offset:2048
	ds_read_b128 v[142:145], v212 offset:3072
	ds_read_b128 v[146:149], v213
	ds_read_b128 v[150:153], v213 offset:1024
	ds_read_b128 v[154:157], v213 offset:2048
	ds_read_b128 v[158:161], v213 offset:3072
	s_add_u32 s40, s38, 0xfff00080
	s_addc_u32 s41, s39, -1
	s_cmp_eq_u32 s73, 60
	s_cselect_b32 s43, s31, s41
	s_cselect_b32 s42, s69, s40
	s_cselect_b32 s41, s29, s72
	s_cselect_b32 s40, s70, s71
	v_lshl_add_u64 v[216:217], s[38:39], 0, v[178:179]
	s_add_i32 m0, s19, 0xc000
	ds_read_b128 v[162:165], v214
	ds_read_b128 v[166:169], v214 offset:1024
	ds_read_b128 v[186:189], v214 offset:2048
	ds_read_b128 v[190:193], v214 offset:3072
	ds_read_b128 v[194:197], v214 offset:4096
	ds_read_b128 v[198:201], v214 offset:5120
	ds_read_b128 v[202:205], v214 offset:6144
	ds_read_b128 v[206:209], v214 offset:7168
	global_load_lds_dwordx4 v[216:217], off
	v_lshl_add_u64 v[216:217], s[38:39], 0, v[180:181]
	s_add_i32 m0, s19, 0xe000
	s_nop 0
	global_load_lds_dwordx4 v[216:217], off
	s_waitcnt vmcnt(8)
	s_waitcnt lgkmcnt(0)
	s_barrier
	v_mfma_f32_16x16x32_bf16 v[126:129], v[130:133], v[162:165], 0
	v_mfma_f32_16x16x32_bf16 v[122:125], v[138:141], v[162:165], 0
	v_mfma_f32_16x16x32_bf16 v[110:113], v[130:133], v[186:189], 0
	v_mfma_f32_16x16x32_bf16 v[106:109], v[138:141], v[186:189], 0
	v_mfma_f32_16x16x32_bf16 v[94:97], v[130:133], v[194:197], 0
	v_mfma_f32_16x16x32_bf16 v[90:93], v[138:141], v[194:197], 0
	v_mfma_f32_16x16x32_bf16 v[78:81], v[130:133], v[202:205], 0
	v_mfma_f32_16x16x32_bf16 v[74:77], v[138:141], v[202:205], 0
	v_mfma_f32_16x16x32_bf16 v[126:129], v[134:137], v[166:169], v[126:129]
	v_mfma_f32_16x16x32_bf16 v[122:125], v[142:145], v[166:169], v[122:125]
	v_mfma_f32_16x16x32_bf16 v[110:113], v[134:137], v[190:193], v[110:113]
	v_mfma_f32_16x16x32_bf16 v[106:109], v[142:145], v[190:193], v[106:109]
	v_mfma_f32_16x16x32_bf16 v[94:97], v[134:137], v[198:201], v[94:97]
	v_mfma_f32_16x16x32_bf16 v[90:93], v[142:145], v[198:201], v[90:93]
	v_mfma_f32_16x16x32_bf16 v[78:81], v[134:137], v[206:209], v[78:81]
	v_mfma_f32_16x16x32_bf16 v[74:77], v[142:145], v[206:209], v[74:77]
	v_mfma_f32_16x16x32_bf16 v[118:121], v[146:149], v[162:165], 0
	v_mfma_f32_16x16x32_bf16 v[114:117], v[154:157], v[162:165], 0
	v_mfma_f32_16x16x32_bf16 v[102:105], v[146:149], v[186:189], 0
	v_mfma_f32_16x16x32_bf16 v[98:101], v[154:157], v[186:189], 0
	v_mfma_f32_16x16x32_bf16 v[86:89], v[146:149], v[194:197], 0
	v_mfma_f32_16x16x32_bf16 v[82:85], v[154:157], v[194:197], 0
	v_mfma_f32_16x16x32_bf16 v[70:73], v[146:149], v[202:205], 0
	v_mfma_f32_16x16x32_bf16 v[66:69], v[154:157], v[202:205], 0
	v_mfma_f32_16x16x32_bf16 v[118:121], v[150:153], v[166:169], v[118:121]
	v_mfma_f32_16x16x32_bf16 v[114:117], v[158:161], v[166:169], v[114:117]
	v_mfma_f32_16x16x32_bf16 v[102:105], v[150:153], v[190:193], v[102:105]
	v_mfma_f32_16x16x32_bf16 v[98:101], v[158:161], v[190:193], v[98:101]
	v_mfma_f32_16x16x32_bf16 v[86:89], v[150:153], v[198:201], v[86:89]
	v_mfma_f32_16x16x32_bf16 v[82:85], v[158:161], v[198:201], v[82:85]
	v_mfma_f32_16x16x32_bf16 v[70:73], v[150:153], v[206:209], v[70:73]
	v_mfma_f32_16x16x32_bf16 v[66:69], v[158:161], v[206:209], v[66:69]
	s_barrier
	s_add_i32 s76, s57, s17
	v_lshl_add_u64 v[216:217], s[40:41], 0, v[172:173]
	s_mov_b32 m0, s76
	ds_read_b128 v[162:165], v214 offset:16384
	ds_read_b128 v[166:169], v214 offset:17408
	ds_read_b128 v[186:189], v214 offset:18432
	ds_read_b128 v[190:193], v214 offset:19456
	ds_read_b128 v[194:197], v214 offset:20480
	ds_read_b128 v[198:201], v214 offset:21504
	ds_read_b128 v[202:205], v214 offset:22528
	ds_read_b128 v[206:209], v214 offset:23552
	global_load_lds_dwordx4 v[216:217], off
	s_add_i32 m0, s76, 0x2000
	s_add_u32 s76, s40, 0x100000
	v_lshl_add_u64 v[218:219], s[40:41], 0, v[176:177]
	s_addc_u32 s77, s41, 0
	s_add_i32 s78, s60, s17
	global_load_lds_dwordx4 v[218:219], off
	v_lshl_add_u64 v[220:221], s[76:77], 0, v[172:173]
	s_mov_b32 m0, s78
	v_lshl_add_u64 v[222:223], s[42:43], 0, v[174:175]
	global_load_lds_dwordx4 v[220:221], off
	v_lshl_add_u64 v[220:221], s[76:77], 0, v[176:177]
	s_add_i32 m0, s78, 0x2000
	s_nop 0
	global_load_lds_dwordx4 v[220:221], off
	v_lshl_add_u64 v[220:221], s[42:43], 0, v[170:171]
	s_mov_b32 m0, s19
	s_nop 0
	global_load_lds_dwordx4 v[220:221], off
	s_mov_b32 m0, s44
	s_nop 0
	global_load_lds_dwordx4 v[222:223], off
	s_waitcnt vmcnt(8)
	s_waitcnt lgkmcnt(0)
	s_barrier
	v_mfma_f32_16x16x32_bf16 v[62:65], v[130:133], v[162:165], 0
	v_mfma_f32_16x16x32_bf16 v[58:61], v[138:141], v[162:165], 0
	v_mfma_f32_16x16x32_bf16 v[46:49], v[130:133], v[186:189], 0
	v_mfma_f32_16x16x32_bf16 v[42:45], v[138:141], v[186:189], 0
	v_mfma_f32_16x16x32_bf16 v[30:33], v[130:133], v[194:197], 0
	v_mfma_f32_16x16x32_bf16 v[26:29], v[138:141], v[194:197], 0
	v_mfma_f32_16x16x32_bf16 v[14:17], v[130:133], v[202:205], 0
	v_mfma_f32_16x16x32_bf16 v[10:13], v[138:141], v[202:205], 0
	v_mfma_f32_16x16x32_bf16 v[62:65], v[134:137], v[166:169], v[62:65]
	v_mfma_f32_16x16x32_bf16 v[58:61], v[142:145], v[166:169], v[58:61]
	v_mfma_f32_16x16x32_bf16 v[46:49], v[134:137], v[190:193], v[46:49]
	v_mfma_f32_16x16x32_bf16 v[42:45], v[142:145], v[190:193], v[42:45]
	v_mfma_f32_16x16x32_bf16 v[30:33], v[134:137], v[198:201], v[30:33]
	v_mfma_f32_16x16x32_bf16 v[26:29], v[142:145], v[198:201], v[26:29]
	v_mfma_f32_16x16x32_bf16 v[14:17], v[134:137], v[206:209], v[14:17]
	v_mfma_f32_16x16x32_bf16 v[10:13], v[142:145], v[206:209], v[10:13]
	v_mfma_f32_16x16x32_bf16 v[54:57], v[146:149], v[162:165], 0
	v_mfma_f32_16x16x32_bf16 v[50:53], v[154:157], v[162:165], 0
	v_mfma_f32_16x16x32_bf16 v[38:41], v[146:149], v[186:189], 0
	v_mfma_f32_16x16x32_bf16 v[34:37], v[154:157], v[186:189], 0
	v_mfma_f32_16x16x32_bf16 v[22:25], v[146:149], v[194:197], 0
	v_mfma_f32_16x16x32_bf16 v[18:21], v[154:157], v[194:197], 0
	v_mfma_f32_16x16x32_bf16 v[6:9], v[146:149], v[202:205], 0
	v_mfma_f32_16x16x32_bf16 v[2:5], v[154:157], v[202:205], 0
	v_mfma_f32_16x16x32_bf16 v[54:57], v[150:153], v[166:169], v[54:57]
	v_mfma_f32_16x16x32_bf16 v[50:53], v[158:161], v[166:169], v[50:53]
	v_mfma_f32_16x16x32_bf16 v[38:41], v[150:153], v[190:193], v[38:41]
	v_mfma_f32_16x16x32_bf16 v[34:37], v[158:161], v[190:193], v[34:37]
	v_mfma_f32_16x16x32_bf16 v[22:25], v[150:153], v[198:201], v[22:25]
	v_mfma_f32_16x16x32_bf16 v[18:21], v[158:161], v[198:201], v[18:21]
	v_mfma_f32_16x16x32_bf16 v[6:9], v[150:153], v[206:209], v[6:9]
	v_mfma_f32_16x16x32_bf16 v[2:5], v[158:161], v[206:209], v[2:5]
	s_barrier
	s_add_i32 s76, 0, 0x18000
	s_add_i32 s77, 0, 0x1c000
	v_add_u32_e32 v142, s76, v211
	v_add_u32_e32 v158, s77, v211
	ds_read_b128 v[130:133], v142
	ds_read_b128 v[134:137], v142 offset:1024
	ds_read_b128 v[138:141], v142 offset:2048
	ds_read_b128 v[142:145], v142 offset:3072
	ds_read_b128 v[146:149], v158
	ds_read_b128 v[150:153], v158 offset:1024
	ds_read_b128 v[154:157], v158 offset:2048
	ds_read_b128 v[158:161], v158 offset:3072
	s_add_u32 s42, s42, 0x100000
	s_addc_u32 s43, s43, 0
	s_mov_b32 m0, s45
	v_lshl_add_u64 v[224:225], s[42:43], 0, v[170:171]
	ds_read_b128 v[162:165], v214 offset:32768
	ds_read_b128 v[166:169], v214 offset:33792
	ds_read_b128 v[186:189], v214 offset:34816
	ds_read_b128 v[190:193], v214 offset:35840
	ds_read_b128 v[194:197], v214 offset:36864
	ds_read_b128 v[198:201], v214 offset:37888
	ds_read_b128 v[202:205], v214 offset:38912
	ds_read_b128 v[206:209], v214 offset:39936
	global_load_lds_dwordx4 v[224:225], off
	v_lshl_add_u64 v[224:225], s[42:43], 0, v[174:175]
	s_mov_b32 m0, s46
	s_nop 0
	global_load_lds_dwordx4 v[224:225], off
	s_waitcnt vmcnt(8)
	s_waitcnt lgkmcnt(0)
	s_barrier
	v_mfma_f32_16x16x32_bf16 v[126:129], v[130:133], v[162:165], v[126:129]
	v_mfma_f32_16x16x32_bf16 v[122:125], v[138:141], v[162:165], v[122:125]
	v_mfma_f32_16x16x32_bf16 v[110:113], v[130:133], v[186:189], v[110:113]
	v_mfma_f32_16x16x32_bf16 v[106:109], v[138:141], v[186:189], v[106:109]
	v_mfma_f32_16x16x32_bf16 v[94:97], v[130:133], v[194:197], v[94:97]
	v_mfma_f32_16x16x32_bf16 v[90:93], v[138:141], v[194:197], v[90:93]
	v_mfma_f32_16x16x32_bf16 v[78:81], v[130:133], v[202:205], v[78:81]
	v_mfma_f32_16x16x32_bf16 v[74:77], v[138:141], v[202:205], v[74:77]
	v_mfma_f32_16x16x32_bf16 v[126:129], v[134:137], v[166:169], v[126:129]
	v_mfma_f32_16x16x32_bf16 v[122:125], v[142:145], v[166:169], v[122:125]
	v_mfma_f32_16x16x32_bf16 v[110:113], v[134:137], v[190:193], v[110:113]
	v_mfma_f32_16x16x32_bf16 v[106:109], v[142:145], v[190:193], v[106:109]
	v_mfma_f32_16x16x32_bf16 v[94:97], v[134:137], v[198:201], v[94:97]
	v_mfma_f32_16x16x32_bf16 v[90:93], v[142:145], v[198:201], v[90:93]
	v_mfma_f32_16x16x32_bf16 v[78:81], v[134:137], v[206:209], v[78:81]
	v_mfma_f32_16x16x32_bf16 v[74:77], v[142:145], v[206:209], v[74:77]
	v_mfma_f32_16x16x32_bf16 v[118:121], v[146:149], v[162:165], v[118:121]
	v_mfma_f32_16x16x32_bf16 v[114:117], v[154:157], v[162:165], v[114:117]
	v_mfma_f32_16x16x32_bf16 v[102:105], v[146:149], v[186:189], v[102:105]
	v_mfma_f32_16x16x32_bf16 v[98:101], v[154:157], v[186:189], v[98:101]
	v_mfma_f32_16x16x32_bf16 v[86:89], v[146:149], v[194:197], v[86:89]
	v_mfma_f32_16x16x32_bf16 v[82:85], v[154:157], v[194:197], v[82:85]
	v_mfma_f32_16x16x32_bf16 v[70:73], v[146:149], v[202:205], v[70:73]
	v_mfma_f32_16x16x32_bf16 v[66:69], v[154:157], v[202:205], v[66:69]
	v_mfma_f32_16x16x32_bf16 v[118:121], v[150:153], v[166:169], v[118:121]
	v_mfma_f32_16x16x32_bf16 v[114:117], v[158:161], v[166:169], v[114:117]
	v_mfma_f32_16x16x32_bf16 v[102:105], v[150:153], v[190:193], v[102:105]
	v_mfma_f32_16x16x32_bf16 v[98:101], v[158:161], v[190:193], v[98:101]
	v_mfma_f32_16x16x32_bf16 v[86:89], v[150:153], v[198:201], v[86:89]
	v_mfma_f32_16x16x32_bf16 v[82:85], v[158:161], v[198:201], v[82:85]
	v_mfma_f32_16x16x32_bf16 v[70:73], v[150:153], v[206:209], v[70:73]
	v_mfma_f32_16x16x32_bf16 v[66:69], v[158:161], v[206:209], v[66:69]
	s_barrier
	s_add_i32 s42, s76, s17
	v_lshl_add_u64 v[216:217], v[216:217], 0, s[8:9]
	s_mov_b32 m0, s42
	ds_read_b128 v[162:165], v214 offset:49152
	ds_read_b128 v[166:169], v214 offset:50176
	ds_read_b128 v[186:189], v214 offset:51200
	ds_read_b128 v[190:193], v214 offset:52224
	ds_read_b128 v[194:197], v214 offset:53248
	ds_read_b128 v[198:201], v214 offset:54272
	ds_read_b128 v[202:205], v214 offset:55296
	ds_read_b128 v[206:209], v214 offset:56320
	global_load_lds_dwordx4 v[216:217], off
	s_add_i32 m0, s42, 0x2000
	s_add_u32 s40, s40, 0x100080
	v_lshl_add_u64 v[216:217], v[218:219], 0, s[8:9]
	s_addc_u32 s41, s41, 0
	s_add_i32 s42, s77, s17
	global_load_lds_dwordx4 v[216:217], off
	v_lshl_add_u64 v[216:217], s[40:41], 0, v[172:173]
	s_mov_b32 m0, s42
	s_nop 0
	global_load_lds_dwordx4 v[216:217], off
	v_lshl_add_u64 v[216:217], s[40:41], 0, v[176:177]
	s_add_i32 m0, s42, 0x2000
	s_nop 0
	global_load_lds_dwordx4 v[216:217], off
	v_lshl_add_u64 v[216:217], v[220:221], 0, s[8:9]
	s_mov_b32 m0, s50
	s_nop 0
	global_load_lds_dwordx4 v[216:217], off
	v_lshl_add_u64 v[216:217], v[222:223], 0, s[8:9]
	s_mov_b32 m0, s51
	s_nop 0
	global_load_lds_dwordx4 v[216:217], off
	s_waitcnt vmcnt(8)
	s_waitcnt lgkmcnt(0)
	s_barrier
	v_mfma_f32_16x16x32_bf16 v[62:65], v[130:133], v[162:165], v[62:65]
	v_mfma_f32_16x16x32_bf16 v[58:61], v[138:141], v[162:165], v[58:61]
	v_mfma_f32_16x16x32_bf16 v[46:49], v[130:133], v[186:189], v[46:49]
	v_mfma_f32_16x16x32_bf16 v[42:45], v[138:141], v[186:189], v[42:45]
	v_mfma_f32_16x16x32_bf16 v[30:33], v[130:133], v[194:197], v[30:33]
	v_mfma_f32_16x16x32_bf16 v[26:29], v[138:141], v[194:197], v[26:29]
	v_mfma_f32_16x16x32_bf16 v[14:17], v[130:133], v[202:205], v[14:17]
	v_mfma_f32_16x16x32_bf16 v[10:13], v[138:141], v[202:205], v[10:13]
	v_mfma_f32_16x16x32_bf16 v[62:65], v[134:137], v[166:169], v[62:65]
	v_mfma_f32_16x16x32_bf16 v[58:61], v[142:145], v[166:169], v[58:61]
	v_mfma_f32_16x16x32_bf16 v[46:49], v[134:137], v[190:193], v[46:49]
	v_mfma_f32_16x16x32_bf16 v[42:45], v[142:145], v[190:193], v[42:45]
	v_mfma_f32_16x16x32_bf16 v[30:33], v[134:137], v[198:201], v[30:33]
	v_mfma_f32_16x16x32_bf16 v[26:29], v[142:145], v[198:201], v[26:29]
	v_mfma_f32_16x16x32_bf16 v[14:17], v[134:137], v[206:209], v[14:17]
	v_mfma_f32_16x16x32_bf16 v[10:13], v[142:145], v[206:209], v[10:13]
	v_mfma_f32_16x16x32_bf16 v[54:57], v[146:149], v[162:165], v[54:57]
	v_mfma_f32_16x16x32_bf16 v[50:53], v[154:157], v[162:165], v[50:53]
	v_mfma_f32_16x16x32_bf16 v[38:41], v[146:149], v[186:189], v[38:41]
	v_mfma_f32_16x16x32_bf16 v[34:37], v[154:157], v[186:189], v[34:37]
	v_mfma_f32_16x16x32_bf16 v[22:25], v[146:149], v[194:197], v[22:25]
	v_mfma_f32_16x16x32_bf16 v[18:21], v[154:157], v[194:197], v[18:21]
	v_mfma_f32_16x16x32_bf16 v[6:9], v[146:149], v[202:205], v[6:9]
	v_mfma_f32_16x16x32_bf16 v[2:5], v[154:157], v[202:205], v[2:5]
	v_mfma_f32_16x16x32_bf16 v[54:57], v[150:153], v[166:169], v[54:57]
	v_mfma_f32_16x16x32_bf16 v[50:53], v[158:161], v[166:169], v[50:53]
	v_mfma_f32_16x16x32_bf16 v[38:41], v[150:153], v[190:193], v[38:41]
	v_mfma_f32_16x16x32_bf16 v[34:37], v[158:161], v[190:193], v[34:37]
	v_mfma_f32_16x16x32_bf16 v[22:25], v[150:153], v[198:201], v[22:25]
	v_mfma_f32_16x16x32_bf16 v[18:21], v[158:161], v[198:201], v[18:21]
	v_mfma_f32_16x16x32_bf16 v[6:9], v[150:153], v[206:209], v[6:9]
	v_mfma_f32_16x16x32_bf16 v[2:5], v[158:161], v[206:209], v[2:5]
	s_barrier
	s_add_i32 s73, s73, 2
	s_add_u32 s38, s38, 0x100
	s_addc_u32 s39, s39, 0
	s_add_u32 s71, s71, 0x100
	s_addc_u32 s72, s72, 0
	s_cmp_gt_u32 s73, 61

.LBB0_2055:
	s_ashr_i32 s31, s30, 31
	s_lshl_b64 s[18:19], s[30:31], 20
	s_add_u32 s34, s27, s18
	s_addc_u32 s35, s44, s19
	s_and_b64 s[18:19], s[0:1], exec
	s_cselect_b32 s31, s35, s3
	s_cselect_b32 s87, s34, s2
	s_ashr_i32 s29, s28, 31
	s_lshl_b64 s[18:19], s[28:29], 20
	s_add_u32 s36, s45, s18
	s_addc_u32 s37, s46, s19
	s_and_b64 s[18:19], s[0:1], exec
	s_cselect_b32 s29, s37, s5
	s_cselect_b32 s90, s36, s4
	s_add_u32 s91, s4, 0x100
	s_addc_u32 s92, s5, 0
	s_mov_b32 s93, -2
	ds_read_b128 v[130:133], v234
	ds_read_b128 v[134:137], v234 offset:1024
	ds_read_b128 v[162:165], v234 offset:2048
	ds_read_b128 v[166:169], v234 offset:3072
	ds_read_b128 v[170:173], v235
	ds_read_b128 v[174:177], v235 offset:1024
	ds_read_b128 v[178:181], v235 offset:2048
	ds_read_b128 v[182:185], v235 offset:3072
	s_add_u32 s4, s2, 0x100
	s_addc_u32 s5, s3, 0
	s_cmp_eq_u32 s93, 28
	s_cselect_b32 s43, s31, s5
	s_cselect_b32 s42, s87, s4
	s_cselect_b32 s19, s29, s92
	s_cselect_b32 s18, s90, s91
	v_lshl_add_u64 v[218:219], s[2:3], 0, v[154:155]
	s_add_i32 m0, s49, 0xc000
	ds_read_b128 v[186:189], v236
	ds_read_b128 v[190:193], v236 offset:1024
	ds_read_b128 v[194:197], v236 offset:2048
	ds_read_b128 v[198:201], v236 offset:3072
	ds_read_b128 v[202:205], v236 offset:4096
	ds_read_b128 v[206:209], v236 offset:5120
	ds_read_b128 v[210:213], v236 offset:6144
	ds_read_b128 v[214:217], v236 offset:7168
	global_load_lds_dwordx4 v[218:219], off
	v_lshl_add_u64 v[218:219], s[2:3], 0, v[156:157]
	s_add_i32 m0, s49, 0xe000
	s_nop 0
	global_load_lds_dwordx4 v[218:219], off
	s_waitcnt vmcnt(8)
	s_waitcnt lgkmcnt(0)
	s_barrier
	v_mfma_i32_16x16x64_i8 v[118:121], v[130:133], v[186:189], 0
	v_mfma_i32_16x16x64_i8 v[102:105], v[162:165], v[186:189], 0
	v_mfma_i32_16x16x64_i8 v[114:117], v[130:133], v[194:197], 0
	v_mfma_i32_16x16x64_i8 v[98:101], v[162:165], v[194:197], 0
	v_mfma_i32_16x16x64_i8 v[126:129], v[130:133], v[202:205], 0
	v_mfma_i32_16x16x64_i8 v[110:113], v[162:165], v[202:205], 0
	v_mfma_i32_16x16x64_i8 v[122:125], v[130:133], v[210:213], 0
	v_mfma_i32_16x16x64_i8 v[106:109], v[162:165], v[210:213], 0
	v_mfma_i32_16x16x64_i8 v[118:121], v[134:137], v[190:193], v[118:121]
	v_mfma_i32_16x16x64_i8 v[102:105], v[166:169], v[190:193], v[102:105]
	v_mfma_i32_16x16x64_i8 v[114:117], v[134:137], v[198:201], v[114:117]
	v_mfma_i32_16x16x64_i8 v[98:101], v[166:169], v[198:201], v[98:101]
	v_mfma_i32_16x16x64_i8 v[126:129], v[134:137], v[206:209], v[126:129]
	v_mfma_i32_16x16x64_i8 v[110:113], v[166:169], v[206:209], v[110:113]
	v_mfma_i32_16x16x64_i8 v[122:125], v[134:137], v[214:217], v[122:125]
	v_mfma_i32_16x16x64_i8 v[106:109], v[166:169], v[214:217], v[106:109]
	v_mfma_i32_16x16x64_i8 v[86:89], v[170:173], v[186:189], 0
	v_mfma_i32_16x16x64_i8 v[70:73], v[178:181], v[186:189], 0
	v_mfma_i32_16x16x64_i8 v[82:85], v[170:173], v[194:197], 0
	v_mfma_i32_16x16x64_i8 v[66:69], v[178:181], v[194:197], 0
	v_mfma_i32_16x16x64_i8 v[94:97], v[170:173], v[202:205], 0
	v_mfma_i32_16x16x64_i8 v[78:81], v[178:181], v[202:205], 0
	v_mfma_i32_16x16x64_i8 v[90:93], v[170:173], v[210:213], 0
	v_mfma_i32_16x16x64_i8 v[74:77], v[178:181], v[210:213], 0
	v_mfma_i32_16x16x64_i8 v[86:89], v[174:177], v[190:193], v[86:89]
	v_mfma_i32_16x16x64_i8 v[70:73], v[182:185], v[190:193], v[70:73]
	v_mfma_i32_16x16x64_i8 v[82:85], v[174:177], v[198:201], v[82:85]
	v_mfma_i32_16x16x64_i8 v[66:69], v[182:185], v[198:201], v[66:69]
	v_mfma_i32_16x16x64_i8 v[94:97], v[174:177], v[206:209], v[94:97]
	v_mfma_i32_16x16x64_i8 v[78:81], v[182:185], v[206:209], v[78:81]
	v_mfma_i32_16x16x64_i8 v[90:93], v[174:177], v[214:217], v[90:93]
	v_mfma_i32_16x16x64_i8 v[74:77], v[182:185], v[214:217], v[74:77]
	s_barrier
	s_add_i32 s2, s82, s47
	v_lshl_add_u64 v[218:219], s[18:19], 0, v[144:145]
	s_mov_b32 m0, s2
	ds_read_b128 v[186:189], v236 offset:16384
	ds_read_b128 v[190:193], v236 offset:17408
	ds_read_b128 v[194:197], v236 offset:18432
	ds_read_b128 v[198:201], v236 offset:19456
	ds_read_b128 v[202:205], v236 offset:20480
	ds_read_b128 v[206:209], v236 offset:21504
	ds_read_b128 v[210:213], v236 offset:22528
	ds_read_b128 v[214:217], v236 offset:23552
	global_load_lds_dwordx4 v[218:219], off
	s_add_i32 m0, s2, 0x2000
	s_add_u32 s2, s18, 0x80000
	v_lshl_add_u64 v[220:221], s[18:19], 0, v[148:149]
	s_addc_u32 s3, s19, 0
	s_add_i32 s94, s16, s47
	global_load_lds_dwordx4 v[220:221], off
	v_lshl_add_u64 v[222:223], s[2:3], 0, v[144:145]
	s_mov_b32 m0, s94
	v_lshl_add_u64 v[224:225], s[42:43], 0, v[146:147]
	global_load_lds_dwordx4 v[222:223], off
	v_lshl_add_u64 v[222:223], s[2:3], 0, v[148:149]
	s_add_i32 m0, s94, 0x2000
	s_nop 0
	global_load_lds_dwordx4 v[222:223], off
	v_lshl_add_u64 v[222:223], s[42:43], 0, v[142:143]
	s_mov_b32 m0, s49
	s_nop 0
	global_load_lds_dwordx4 v[222:223], off
	s_mov_b32 m0, s50
	s_nop 0
	global_load_lds_dwordx4 v[224:225], off
	s_waitcnt vmcnt(8)
	s_waitcnt lgkmcnt(0)
	s_barrier
	v_mfma_i32_16x16x64_i8 v[54:57], v[130:133], v[186:189], 0
	v_mfma_i32_16x16x64_i8 v[18:21], v[162:165], v[186:189], 0
	v_mfma_i32_16x16x64_i8 v[50:53], v[130:133], v[194:197], 0
	v_mfma_i32_16x16x64_i8 v[22:25], v[162:165], v[194:197], 0
	v_mfma_i32_16x16x64_i8 v[62:65], v[130:133], v[202:205], 0
	v_mfma_i32_16x16x64_i8 v[30:33], v[162:165], v[202:205], 0
	v_mfma_i32_16x16x64_i8 v[58:61], v[130:133], v[210:213], 0
	v_mfma_i32_16x16x64_i8 v[26:29], v[162:165], v[210:213], 0
	v_mfma_i32_16x16x64_i8 v[54:57], v[134:137], v[190:193], v[54:57]
	v_mfma_i32_16x16x64_i8 v[18:21], v[166:169], v[190:193], v[18:21]
	v_mfma_i32_16x16x64_i8 v[50:53], v[134:137], v[198:201], v[50:53]
	v_mfma_i32_16x16x64_i8 v[22:25], v[166:169], v[198:201], v[22:25]
	v_mfma_i32_16x16x64_i8 v[62:65], v[134:137], v[206:209], v[62:65]
	v_mfma_i32_16x16x64_i8 v[30:33], v[166:169], v[206:209], v[30:33]
	v_mfma_i32_16x16x64_i8 v[58:61], v[134:137], v[214:217], v[58:61]
	v_mfma_i32_16x16x64_i8 v[26:29], v[166:169], v[214:217], v[26:29]
	v_mfma_i32_16x16x64_i8 v[46:49], v[170:173], v[186:189], 0
	v_mfma_i32_16x16x64_i8 v[14:17], v[178:181], v[186:189], 0
	v_mfma_i32_16x16x64_i8 v[42:45], v[170:173], v[194:197], 0
	v_mfma_i32_16x16x64_i8 v[10:13], v[178:181], v[194:197], 0
	v_mfma_i32_16x16x64_i8 v[38:41], v[170:173], v[202:205], 0
	v_mfma_i32_16x16x64_i8 v[6:9], v[178:181], v[202:205], 0
	v_mfma_i32_16x16x64_i8 v[34:37], v[170:173], v[210:213], 0
	v_mfma_i32_16x16x64_i8 v[2:5], v[178:181], v[210:213], 0
	v_mfma_i32_16x16x64_i8 v[46:49], v[174:177], v[190:193], v[46:49]
	v_mfma_i32_16x16x64_i8 v[14:17], v[182:185], v[190:193], v[14:17]
	v_mfma_i32_16x16x64_i8 v[42:45], v[174:177], v[198:201], v[42:45]
	v_mfma_i32_16x16x64_i8 v[10:13], v[182:185], v[198:201], v[10:13]
	v_mfma_i32_16x16x64_i8 v[38:41], v[174:177], v[206:209], v[38:41]
	v_mfma_i32_16x16x64_i8 v[6:9], v[182:185], v[206:209], v[6:9]
	v_mfma_i32_16x16x64_i8 v[34:37], v[174:177], v[214:217], v[34:37]
	v_mfma_i32_16x16x64_i8 v[2:5], v[182:185], v[214:217], v[2:5]
	s_barrier
	s_add_i32 s94, 0, 0x18000
	s_add_i32 s95, 0, 0x1c000
	v_add_u32_e32 v166, s94, v232
	v_add_u32_e32 v182, s95, v232
	ds_read_b128 v[130:133], v166
	ds_read_b128 v[134:137], v166 offset:1024
	ds_read_b128 v[162:165], v166 offset:2048
	ds_read_b128 v[166:169], v166 offset:3072
	ds_read_b128 v[170:173], v182
	ds_read_b128 v[174:177], v182 offset:1024
	ds_read_b128 v[178:181], v182 offset:2048
	ds_read_b128 v[182:185], v182 offset:3072
	s_add_u32 s2, s42, 0x80000
	s_addc_u32 s3, s43, 0
	s_mov_b32 m0, s51
	v_lshl_add_u64 v[226:227], s[2:3], 0, v[142:143]
	ds_read_b128 v[186:189], v236 offset:32768
	ds_read_b128 v[190:193], v236 offset:33792
	ds_read_b128 v[194:197], v236 offset:34816
	ds_read_b128 v[198:201], v236 offset:35840
	ds_read_b128 v[202:205], v236 offset:36864
	ds_read_b128 v[206:209], v236 offset:37888
	ds_read_b128 v[210:213], v236 offset:38912
	ds_read_b128 v[214:217], v236 offset:39936
	global_load_lds_dwordx4 v[226:227], off
	v_lshl_add_u64 v[226:227], s[2:3], 0, v[146:147]
	s_mov_b32 m0, s54
	s_nop 0
	global_load_lds_dwordx4 v[226:227], off
	s_waitcnt vmcnt(8)
	s_waitcnt lgkmcnt(0)
	s_barrier
	v_mfma_i32_16x16x64_i8 v[118:121], v[130:133], v[186:189], v[118:121]
	v_mfma_i32_16x16x64_i8 v[102:105], v[162:165], v[186:189], v[102:105]
	v_mfma_i32_16x16x64_i8 v[114:117], v[130:133], v[194:197], v[114:117]
	v_mfma_i32_16x16x64_i8 v[98:101], v[162:165], v[194:197], v[98:101]
	v_mfma_i32_16x16x64_i8 v[126:129], v[130:133], v[202:205], v[126:129]
	v_mfma_i32_16x16x64_i8 v[110:113], v[162:165], v[202:205], v[110:113]
	v_mfma_i32_16x16x64_i8 v[122:125], v[130:133], v[210:213], v[122:125]
	v_mfma_i32_16x16x64_i8 v[106:109], v[162:165], v[210:213], v[106:109]
	v_mfma_i32_16x16x64_i8 v[118:121], v[134:137], v[190:193], v[118:121]
	v_mfma_i32_16x16x64_i8 v[102:105], v[166:169], v[190:193], v[102:105]
	v_mfma_i32_16x16x64_i8 v[114:117], v[134:137], v[198:201], v[114:117]
	v_mfma_i32_16x16x64_i8 v[98:101], v[166:169], v[198:201], v[98:101]
	v_mfma_i32_16x16x64_i8 v[126:129], v[134:137], v[206:209], v[126:129]
	v_mfma_i32_16x16x64_i8 v[110:113], v[166:169], v[206:209], v[110:113]
	v_mfma_i32_16x16x64_i8 v[122:125], v[134:137], v[214:217], v[122:125]
	v_mfma_i32_16x16x64_i8 v[106:109], v[166:169], v[214:217], v[106:109]
	v_mfma_i32_16x16x64_i8 v[86:89], v[170:173], v[186:189], v[86:89]
	v_mfma_i32_16x16x64_i8 v[70:73], v[178:181], v[186:189], v[70:73]
	v_mfma_i32_16x16x64_i8 v[82:85], v[170:173], v[194:197], v[82:85]
	v_mfma_i32_16x16x64_i8 v[66:69], v[178:181], v[194:197], v[66:69]
	v_mfma_i32_16x16x64_i8 v[94:97], v[170:173], v[202:205], v[94:97]
	v_mfma_i32_16x16x64_i8 v[78:81], v[178:181], v[202:205], v[78:81]
	v_mfma_i32_16x16x64_i8 v[90:93], v[170:173], v[210:213], v[90:93]
	v_mfma_i32_16x16x64_i8 v[74:77], v[178:181], v[210:213], v[74:77]
	v_mfma_i32_16x16x64_i8 v[86:89], v[174:177], v[190:193], v[86:89]
	v_mfma_i32_16x16x64_i8 v[70:73], v[182:185], v[190:193], v[70:73]
	v_mfma_i32_16x16x64_i8 v[82:85], v[174:177], v[198:201], v[82:85]
	v_mfma_i32_16x16x64_i8 v[66:69], v[182:185], v[198:201], v[66:69]
	v_mfma_i32_16x16x64_i8 v[94:97], v[174:177], v[206:209], v[94:97]
	v_mfma_i32_16x16x64_i8 v[78:81], v[182:185], v[206:209], v[78:81]
	v_mfma_i32_16x16x64_i8 v[90:93], v[174:177], v[214:217], v[90:93]
	v_mfma_i32_16x16x64_i8 v[74:77], v[182:185], v[214:217], v[74:77]
	s_barrier
	s_add_i32 s2, s94, s47
	v_lshl_add_u64 v[218:219], v[218:219], 0, s[14:15]
	s_mov_b32 m0, s2
	ds_read_b128 v[186:189], v236 offset:49152
	ds_read_b128 v[190:193], v236 offset:50176
	ds_read_b128 v[194:197], v236 offset:51200
	ds_read_b128 v[198:201], v236 offset:52224
	ds_read_b128 v[202:205], v236 offset:53248
	ds_read_b128 v[206:209], v236 offset:54272
	ds_read_b128 v[210:213], v236 offset:55296
	ds_read_b128 v[214:217], v236 offset:56320
	global_load_lds_dwordx4 v[218:219], off
	s_add_i32 m0, s2, 0x2000
	s_add_u32 s2, s18, 0x80080
	v_lshl_add_u64 v[218:219], v[220:221], 0, s[14:15]
	s_addc_u32 s3, s19, 0
	s_add_i32 s18, s95, s47
	global_load_lds_dwordx4 v[218:219], off
	v_lshl_add_u64 v[218:219], s[2:3], 0, v[144:145]
	s_mov_b32 m0, s18
	s_nop 0
	global_load_lds_dwordx4 v[218:219], off
	v_lshl_add_u64 v[218:219], s[2:3], 0, v[148:149]
	s_add_i32 m0, s18, 0x2000
	s_nop 0
	global_load_lds_dwordx4 v[218:219], off
	v_lshl_add_u64 v[218:219], v[222:223], 0, s[14:15]
	s_mov_b32 m0, s63
	s_nop 0
	global_load_lds_dwordx4 v[218:219], off
	v_lshl_add_u64 v[218:219], v[224:225], 0, s[14:15]
	s_mov_b32 m0, s64
	s_nop 0
	global_load_lds_dwordx4 v[218:219], off
	s_waitcnt vmcnt(8)
	s_waitcnt lgkmcnt(0)
	s_barrier
	v_mfma_i32_16x16x64_i8 v[54:57], v[130:133], v[186:189], v[54:57]
	v_mfma_i32_16x16x64_i8 v[18:21], v[162:165], v[186:189], v[18:21]
	v_mfma_i32_16x16x64_i8 v[50:53], v[130:133], v[194:197], v[50:53]
	v_mfma_i32_16x16x64_i8 v[22:25], v[162:165], v[194:197], v[22:25]
	v_mfma_i32_16x16x64_i8 v[62:65], v[130:133], v[202:205], v[62:65]
	v_mfma_i32_16x16x64_i8 v[30:33], v[162:165], v[202:205], v[30:33]
	v_mfma_i32_16x16x64_i8 v[58:61], v[130:133], v[210:213], v[58:61]
	v_mfma_i32_16x16x64_i8 v[26:29], v[162:165], v[210:213], v[26:29]
	v_mfma_i32_16x16x64_i8 v[54:57], v[134:137], v[190:193], v[54:57]
	v_mfma_i32_16x16x64_i8 v[18:21], v[166:169], v[190:193], v[18:21]
	v_mfma_i32_16x16x64_i8 v[50:53], v[134:137], v[198:201], v[50:53]
	v_mfma_i32_16x16x64_i8 v[22:25], v[166:169], v[198:201], v[22:25]
	v_mfma_i32_16x16x64_i8 v[62:65], v[134:137], v[206:209], v[62:65]
	v_mfma_i32_16x16x64_i8 v[30:33], v[166:169], v[206:209], v[30:33]
	v_mfma_i32_16x16x64_i8 v[58:61], v[134:137], v[214:217], v[58:61]
	v_mfma_i32_16x16x64_i8 v[26:29], v[166:169], v[214:217], v[26:29]
	v_mfma_i32_16x16x64_i8 v[46:49], v[170:173], v[186:189], v[46:49]
	v_mfma_i32_16x16x64_i8 v[14:17], v[178:181], v[186:189], v[14:17]
	v_mfma_i32_16x16x64_i8 v[42:45], v[170:173], v[194:197], v[42:45]
	v_mfma_i32_16x16x64_i8 v[10:13], v[178:181], v[194:197], v[10:13]
	v_mfma_i32_16x16x64_i8 v[38:41], v[170:173], v[202:205], v[38:41]
	v_mfma_i32_16x16x64_i8 v[6:9], v[178:181], v[202:205], v[6:9]
	v_mfma_i32_16x16x64_i8 v[34:37], v[170:173], v[210:213], v[34:37]
	v_mfma_i32_16x16x64_i8 v[2:5], v[178:181], v[210:213], v[2:5]
	v_mfma_i32_16x16x64_i8 v[46:49], v[174:177], v[190:193], v[46:49]
	v_mfma_i32_16x16x64_i8 v[14:17], v[182:185], v[190:193], v[14:17]
	v_mfma_i32_16x16x64_i8 v[42:45], v[174:177], v[198:201], v[42:45]
	v_mfma_i32_16x16x64_i8 v[10:13], v[182:185], v[198:201], v[10:13]
	v_mfma_i32_16x16x64_i8 v[38:41], v[174:177], v[206:209], v[38:41]
	v_mfma_i32_16x16x64_i8 v[6:9], v[182:185], v[206:209], v[6:9]
	v_mfma_i32_16x16x64_i8 v[34:37], v[174:177], v[214:217], v[34:37]
	v_mfma_i32_16x16x64_i8 v[2:5], v[182:185], v[214:217], v[2:5]
	s_barrier
	s_add_i32 s93, s93, 2
	s_add_u32 s91, s91, 0x100
	s_addc_u32 s92, s92, 0
	s_cmp_gt_u32 s93, 29
	s_mov_b64 s[2:3], s[4:5]

.LBB0_2240:
	s_add_u32 s69, s36, 0x100
	s_addc_u32 s70, s37, 0
	s_mov_b32 s71, -2
	ds_read_b128 v[130:133], v212
	ds_read_b128 v[134:137], v212 offset:1024
	ds_read_b128 v[138:141], v212 offset:2048
	ds_read_b128 v[142:145], v212 offset:3072
	ds_read_b128 v[146:149], v213
	ds_read_b128 v[150:153], v213 offset:1024
	ds_read_b128 v[154:157], v213 offset:2048
	ds_read_b128 v[158:161], v213 offset:3072
	s_add_u32 s36, s18, 0x100
	s_addc_u32 s37, s19, 0
	s_cmpk_eq_i32 s71, 0xdc
	s_cselect_b32 s41, s3, s37
	s_cselect_b32 s40, s2, s36
	s_cselect_b32 s39, s35, s70
	s_cselect_b32 s38, s34, s69
	v_lshl_add_u64 v[216:217], s[18:19], 0, v[178:179]
	s_add_i32 m0, s44, 0xc000
	ds_read_b128 v[162:165], v214
	ds_read_b128 v[166:169], v214 offset:1024
	ds_read_b128 v[186:189], v214 offset:2048
	ds_read_b128 v[190:193], v214 offset:3072
	ds_read_b128 v[194:197], v214 offset:4096
	ds_read_b128 v[198:201], v214 offset:5120
	ds_read_b128 v[202:205], v214 offset:6144
	ds_read_b128 v[206:209], v214 offset:7168
	global_load_lds_dwordx4 v[216:217], off
	v_lshl_add_u64 v[216:217], s[18:19], 0, v[180:181]
	s_add_i32 m0, s44, 0xe000
	s_nop 0
	global_load_lds_dwordx4 v[216:217], off
	s_waitcnt vmcnt(8)
	s_waitcnt lgkmcnt(0)
	s_barrier
	v_mfma_f32_16x16x32_bf16 v[126:129], v[130:133], v[162:165], 0
	v_mfma_f32_16x16x32_bf16 v[122:125], v[138:141], v[162:165], 0
	v_mfma_f32_16x16x32_bf16 v[110:113], v[130:133], v[186:189], 0
	v_mfma_f32_16x16x32_bf16 v[106:109], v[138:141], v[186:189], 0
	v_mfma_f32_16x16x32_bf16 v[94:97], v[130:133], v[194:197], 0
	v_mfma_f32_16x16x32_bf16 v[90:93], v[138:141], v[194:197], 0
	v_mfma_f32_16x16x32_bf16 v[78:81], v[130:133], v[202:205], 0
	v_mfma_f32_16x16x32_bf16 v[74:77], v[138:141], v[202:205], 0
	v_mfma_f32_16x16x32_bf16 v[126:129], v[134:137], v[166:169], v[126:129]
	v_mfma_f32_16x16x32_bf16 v[122:125], v[142:145], v[166:169], v[122:125]
	v_mfma_f32_16x16x32_bf16 v[110:113], v[134:137], v[190:193], v[110:113]
	v_mfma_f32_16x16x32_bf16 v[106:109], v[142:145], v[190:193], v[106:109]
	v_mfma_f32_16x16x32_bf16 v[94:97], v[134:137], v[198:201], v[94:97]
	v_mfma_f32_16x16x32_bf16 v[90:93], v[142:145], v[198:201], v[90:93]
	v_mfma_f32_16x16x32_bf16 v[78:81], v[134:137], v[206:209], v[78:81]
	v_mfma_f32_16x16x32_bf16 v[74:77], v[142:145], v[206:209], v[74:77]
	v_mfma_f32_16x16x32_bf16 v[118:121], v[146:149], v[162:165], 0
	v_mfma_f32_16x16x32_bf16 v[114:117], v[154:157], v[162:165], 0
	v_mfma_f32_16x16x32_bf16 v[102:105], v[146:149], v[186:189], 0
	v_mfma_f32_16x16x32_bf16 v[98:101], v[154:157], v[186:189], 0
	v_mfma_f32_16x16x32_bf16 v[86:89], v[146:149], v[194:197], 0
	v_mfma_f32_16x16x32_bf16 v[82:85], v[154:157], v[194:197], 0
	v_mfma_f32_16x16x32_bf16 v[70:73], v[146:149], v[202:205], 0
	v_mfma_f32_16x16x32_bf16 v[66:69], v[154:157], v[202:205], 0
	v_mfma_f32_16x16x32_bf16 v[118:121], v[150:153], v[166:169], v[118:121]
	v_mfma_f32_16x16x32_bf16 v[114:117], v[158:161], v[166:169], v[114:117]
	v_mfma_f32_16x16x32_bf16 v[102:105], v[150:153], v[190:193], v[102:105]
	v_mfma_f32_16x16x32_bf16 v[98:101], v[158:161], v[190:193], v[98:101]
	v_mfma_f32_16x16x32_bf16 v[86:89], v[150:153], v[198:201], v[86:89]
	v_mfma_f32_16x16x32_bf16 v[82:85], v[158:161], v[198:201], v[82:85]
	v_mfma_f32_16x16x32_bf16 v[70:73], v[150:153], v[206:209], v[70:73]
	v_mfma_f32_16x16x32_bf16 v[66:69], v[158:161], v[206:209], v[66:69]
	s_barrier
	s_add_i32 s18, s56, s43
	v_lshl_add_u64 v[216:217], s[38:39], 0, v[172:173]
	s_mov_b32 m0, s18
	ds_read_b128 v[162:165], v214 offset:16384
	ds_read_b128 v[166:169], v214 offset:17408
	ds_read_b128 v[186:189], v214 offset:18432
	ds_read_b128 v[190:193], v214 offset:19456
	ds_read_b128 v[194:197], v214 offset:20480
	ds_read_b128 v[198:201], v214 offset:21504
	ds_read_b128 v[202:205], v214 offset:22528
	ds_read_b128 v[206:209], v214 offset:23552
	global_load_lds_dwordx4 v[216:217], off
	s_add_i32 m0, s18, 0x2000
	s_add_u32 s18, s38, 0x380000
	v_lshl_add_u64 v[218:219], s[38:39], 0, v[176:177]
	s_addc_u32 s19, s39, 0
	s_add_i32 s72, s57, s43
	global_load_lds_dwordx4 v[218:219], off
	v_lshl_add_u64 v[220:221], s[18:19], 0, v[172:173]
	s_mov_b32 m0, s72
	v_lshl_add_u64 v[222:223], s[40:41], 0, v[174:175]
	global_load_lds_dwordx4 v[220:221], off
	v_lshl_add_u64 v[220:221], s[18:19], 0, v[176:177]
	s_add_i32 m0, s72, 0x2000
	s_nop 0
	global_load_lds_dwordx4 v[220:221], off
	v_lshl_add_u64 v[220:221], s[40:41], 0, v[170:171]
	s_mov_b32 m0, s44
	s_nop 0
	global_load_lds_dwordx4 v[220:221], off
	s_mov_b32 m0, s45
	s_nop 0
	global_load_lds_dwordx4 v[222:223], off
	s_waitcnt vmcnt(8)
	s_waitcnt lgkmcnt(0)
	s_barrier
	v_mfma_f32_16x16x32_bf16 v[62:65], v[130:133], v[162:165], 0
	v_mfma_f32_16x16x32_bf16 v[58:61], v[138:141], v[162:165], 0
	v_mfma_f32_16x16x32_bf16 v[46:49], v[130:133], v[186:189], 0
	v_mfma_f32_16x16x32_bf16 v[42:45], v[138:141], v[186:189], 0
	v_mfma_f32_16x16x32_bf16 v[30:33], v[130:133], v[194:197], 0
	v_mfma_f32_16x16x32_bf16 v[26:29], v[138:141], v[194:197], 0
	v_mfma_f32_16x16x32_bf16 v[14:17], v[130:133], v[202:205], 0
	v_mfma_f32_16x16x32_bf16 v[10:13], v[138:141], v[202:205], 0
	v_mfma_f32_16x16x32_bf16 v[62:65], v[134:137], v[166:169], v[62:65]
	v_mfma_f32_16x16x32_bf16 v[58:61], v[142:145], v[166:169], v[58:61]
	v_mfma_f32_16x16x32_bf16 v[46:49], v[134:137], v[190:193], v[46:49]
	v_mfma_f32_16x16x32_bf16 v[42:45], v[142:145], v[190:193], v[42:45]
	v_mfma_f32_16x16x32_bf16 v[30:33], v[134:137], v[198:201], v[30:33]
	v_mfma_f32_16x16x32_bf16 v[26:29], v[142:145], v[198:201], v[26:29]
	v_mfma_f32_16x16x32_bf16 v[14:17], v[134:137], v[206:209], v[14:17]
	v_mfma_f32_16x16x32_bf16 v[10:13], v[142:145], v[206:209], v[10:13]
	v_mfma_f32_16x16x32_bf16 v[54:57], v[146:149], v[162:165], 0
	v_mfma_f32_16x16x32_bf16 v[50:53], v[154:157], v[162:165], 0
	v_mfma_f32_16x16x32_bf16 v[38:41], v[146:149], v[186:189], 0
	v_mfma_f32_16x16x32_bf16 v[34:37], v[154:157], v[186:189], 0
	v_mfma_f32_16x16x32_bf16 v[22:25], v[146:149], v[194:197], 0
	v_mfma_f32_16x16x32_bf16 v[18:21], v[154:157], v[194:197], 0
	v_mfma_f32_16x16x32_bf16 v[6:9], v[146:149], v[202:205], 0
	v_mfma_f32_16x16x32_bf16 v[2:5], v[154:157], v[202:205], 0
	v_mfma_f32_16x16x32_bf16 v[54:57], v[150:153], v[166:169], v[54:57]
	v_mfma_f32_16x16x32_bf16 v[50:53], v[158:161], v[166:169], v[50:53]
	v_mfma_f32_16x16x32_bf16 v[38:41], v[150:153], v[190:193], v[38:41]
	v_mfma_f32_16x16x32_bf16 v[34:37], v[158:161], v[190:193], v[34:37]
	v_mfma_f32_16x16x32_bf16 v[22:25], v[150:153], v[198:201], v[22:25]
	v_mfma_f32_16x16x32_bf16 v[18:21], v[158:161], v[198:201], v[18:21]
	v_mfma_f32_16x16x32_bf16 v[6:9], v[150:153], v[206:209], v[6:9]
	v_mfma_f32_16x16x32_bf16 v[2:5], v[158:161], v[206:209], v[2:5]
	s_barrier
	s_add_i32 s72, 0, 0x18000
	s_add_i32 s73, 0, 0x1c000
	v_add_u32_e32 v142, s72, v211
	v_add_u32_e32 v158, s73, v211
	ds_read_b128 v[130:133], v142
	ds_read_b128 v[134:137], v142 offset:1024
	ds_read_b128 v[138:141], v142 offset:2048
	ds_read_b128 v[142:145], v142 offset:3072
	ds_read_b128 v[146:149], v158
	ds_read_b128 v[150:153], v158 offset:1024
	ds_read_b128 v[154:157], v158 offset:2048
	ds_read_b128 v[158:161], v158 offset:3072
	s_add_u32 s18, s40, 0x380000
	s_addc_u32 s19, s41, 0
	s_mov_b32 m0, s46
	v_lshl_add_u64 v[224:225], s[18:19], 0, v[170:171]
	ds_read_b128 v[162:165], v214 offset:32768
	ds_read_b128 v[166:169], v214 offset:33792
	ds_read_b128 v[186:189], v214 offset:34816
	ds_read_b128 v[190:193], v214 offset:35840
	ds_read_b128 v[194:197], v214 offset:36864
	ds_read_b128 v[198:201], v214 offset:37888
	ds_read_b128 v[202:205], v214 offset:38912
	ds_read_b128 v[206:209], v214 offset:39936
	global_load_lds_dwordx4 v[224:225], off
	v_lshl_add_u64 v[224:225], s[18:19], 0, v[174:175]
	s_mov_b32 m0, s47
	s_nop 0
	global_load_lds_dwordx4 v[224:225], off
	s_waitcnt vmcnt(8)
	s_waitcnt lgkmcnt(0)
	s_barrier
	v_mfma_f32_16x16x32_bf16 v[126:129], v[130:133], v[162:165], v[126:129]
	v_mfma_f32_16x16x32_bf16 v[122:125], v[138:141], v[162:165], v[122:125]
	v_mfma_f32_16x16x32_bf16 v[110:113], v[130:133], v[186:189], v[110:113]
	v_mfma_f32_16x16x32_bf16 v[106:109], v[138:141], v[186:189], v[106:109]
	v_mfma_f32_16x16x32_bf16 v[94:97], v[130:133], v[194:197], v[94:97]
	v_mfma_f32_16x16x32_bf16 v[90:93], v[138:141], v[194:197], v[90:93]
	v_mfma_f32_16x16x32_bf16 v[78:81], v[130:133], v[202:205], v[78:81]
	v_mfma_f32_16x16x32_bf16 v[74:77], v[138:141], v[202:205], v[74:77]
	v_mfma_f32_16x16x32_bf16 v[126:129], v[134:137], v[166:169], v[126:129]
	v_mfma_f32_16x16x32_bf16 v[122:125], v[142:145], v[166:169], v[122:125]
	v_mfma_f32_16x16x32_bf16 v[110:113], v[134:137], v[190:193], v[110:113]
	v_mfma_f32_16x16x32_bf16 v[106:109], v[142:145], v[190:193], v[106:109]
	v_mfma_f32_16x16x32_bf16 v[94:97], v[134:137], v[198:201], v[94:97]
	v_mfma_f32_16x16x32_bf16 v[90:93], v[142:145], v[198:201], v[90:93]
	v_mfma_f32_16x16x32_bf16 v[78:81], v[134:137], v[206:209], v[78:81]
	v_mfma_f32_16x16x32_bf16 v[74:77], v[142:145], v[206:209], v[74:77]
	v_mfma_f32_16x16x32_bf16 v[118:121], v[146:149], v[162:165], v[118:121]
	v_mfma_f32_16x16x32_bf16 v[114:117], v[154:157], v[162:165], v[114:117]
	v_mfma_f32_16x16x32_bf16 v[102:105], v[146:149], v[186:189], v[102:105]
	v_mfma_f32_16x16x32_bf16 v[98:101], v[154:157], v[186:189], v[98:101]
	v_mfma_f32_16x16x32_bf16 v[86:89], v[146:149], v[194:197], v[86:89]
	v_mfma_f32_16x16x32_bf16 v[82:85], v[154:157], v[194:197], v[82:85]
	v_mfma_f32_16x16x32_bf16 v[70:73], v[146:149], v[202:205], v[70:73]
	v_mfma_f32_16x16x32_bf16 v[66:69], v[154:157], v[202:205], v[66:69]
	v_mfma_f32_16x16x32_bf16 v[118:121], v[150:153], v[166:169], v[118:121]
	v_mfma_f32_16x16x32_bf16 v[114:117], v[158:161], v[166:169], v[114:117]
	v_mfma_f32_16x16x32_bf16 v[102:105], v[150:153], v[190:193], v[102:105]
	v_mfma_f32_16x16x32_bf16 v[98:101], v[158:161], v[190:193], v[98:101]
	v_mfma_f32_16x16x32_bf16 v[86:89], v[150:153], v[198:201], v[86:89]
	v_mfma_f32_16x16x32_bf16 v[82:85], v[158:161], v[198:201], v[82:85]
	v_mfma_f32_16x16x32_bf16 v[70:73], v[150:153], v[206:209], v[70:73]
	v_mfma_f32_16x16x32_bf16 v[66:69], v[158:161], v[206:209], v[66:69]
	s_barrier
	s_add_i32 s18, s72, s43
	v_lshl_add_u64 v[216:217], v[216:217], 0, s[8:9]
	s_mov_b32 m0, s18
	ds_read_b128 v[162:165], v214 offset:49152
	ds_read_b128 v[166:169], v214 offset:50176
	ds_read_b128 v[186:189], v214 offset:51200
	ds_read_b128 v[190:193], v214 offset:52224
	ds_read_b128 v[194:197], v214 offset:53248
	ds_read_b128 v[198:201], v214 offset:54272
	ds_read_b128 v[202:205], v214 offset:55296
	ds_read_b128 v[206:209], v214 offset:56320
	global_load_lds_dwordx4 v[216:217], off
	s_add_i32 m0, s18, 0x2000
	s_add_u32 s18, s38, 0x380080
	v_lshl_add_u64 v[216:217], v[218:219], 0, s[8:9]
	s_addc_u32 s19, s39, 0
	s_add_i32 s38, s73, s43
	global_load_lds_dwordx4 v[216:217], off
	v_lshl_add_u64 v[216:217], s[18:19], 0, v[172:173]
	s_mov_b32 m0, s38
	s_nop 0
	global_load_lds_dwordx4 v[216:217], off
	v_lshl_add_u64 v[216:217], s[18:19], 0, v[176:177]
	s_add_i32 m0, s38, 0x2000
	s_nop 0
	global_load_lds_dwordx4 v[216:217], off
	v_lshl_add_u64 v[216:217], v[220:221], 0, s[8:9]
	s_mov_b32 m0, s51
	s_nop 0
	global_load_lds_dwordx4 v[216:217], off
	v_lshl_add_u64 v[216:217], v[222:223], 0, s[8:9]
	s_mov_b32 m0, s54
	s_nop 0
	global_load_lds_dwordx4 v[216:217], off
	s_waitcnt vmcnt(8)
	s_waitcnt lgkmcnt(0)
	s_barrier
	v_mfma_f32_16x16x32_bf16 v[62:65], v[130:133], v[162:165], v[62:65]
	v_mfma_f32_16x16x32_bf16 v[58:61], v[138:141], v[162:165], v[58:61]
	v_mfma_f32_16x16x32_bf16 v[46:49], v[130:133], v[186:189], v[46:49]
	v_mfma_f32_16x16x32_bf16 v[42:45], v[138:141], v[186:189], v[42:45]
	v_mfma_f32_16x16x32_bf16 v[30:33], v[130:133], v[194:197], v[30:33]
	v_mfma_f32_16x16x32_bf16 v[26:29], v[138:141], v[194:197], v[26:29]
	v_mfma_f32_16x16x32_bf16 v[14:17], v[130:133], v[202:205], v[14:17]
	v_mfma_f32_16x16x32_bf16 v[10:13], v[138:141], v[202:205], v[10:13]
	v_mfma_f32_16x16x32_bf16 v[62:65], v[134:137], v[166:169], v[62:65]
	v_mfma_f32_16x16x32_bf16 v[58:61], v[142:145], v[166:169], v[58:61]
	v_mfma_f32_16x16x32_bf16 v[46:49], v[134:137], v[190:193], v[46:49]
	v_mfma_f32_16x16x32_bf16 v[42:45], v[142:145], v[190:193], v[42:45]
	v_mfma_f32_16x16x32_bf16 v[30:33], v[134:137], v[198:201], v[30:33]
	v_mfma_f32_16x16x32_bf16 v[26:29], v[142:145], v[198:201], v[26:29]
	v_mfma_f32_16x16x32_bf16 v[14:17], v[134:137], v[206:209], v[14:17]
	v_mfma_f32_16x16x32_bf16 v[10:13], v[142:145], v[206:209], v[10:13]
	v_mfma_f32_16x16x32_bf16 v[54:57], v[146:149], v[162:165], v[54:57]
	v_mfma_f32_16x16x32_bf16 v[50:53], v[154:157], v[162:165], v[50:53]
	v_mfma_f32_16x16x32_bf16 v[38:41], v[146:149], v[186:189], v[38:41]
	v_mfma_f32_16x16x32_bf16 v[34:37], v[154:157], v[186:189], v[34:37]
	v_mfma_f32_16x16x32_bf16 v[22:25], v[146:149], v[194:197], v[22:25]
	v_mfma_f32_16x16x32_bf16 v[18:21], v[154:157], v[194:197], v[18:21]
	v_mfma_f32_16x16x32_bf16 v[6:9], v[146:149], v[202:205], v[6:9]
	v_mfma_f32_16x16x32_bf16 v[2:5], v[154:157], v[202:205], v[2:5]
	v_mfma_f32_16x16x32_bf16 v[54:57], v[150:153], v[166:169], v[54:57]
	v_mfma_f32_16x16x32_bf16 v[50:53], v[158:161], v[166:169], v[50:53]
	v_mfma_f32_16x16x32_bf16 v[38:41], v[150:153], v[190:193], v[38:41]
	v_mfma_f32_16x16x32_bf16 v[34:37], v[158:161], v[190:193], v[34:37]
	v_mfma_f32_16x16x32_bf16 v[22:25], v[150:153], v[198:201], v[22:25]
	v_mfma_f32_16x16x32_bf16 v[18:21], v[158:161], v[198:201], v[18:21]
	v_mfma_f32_16x16x32_bf16 v[6:9], v[150:153], v[206:209], v[6:9]
	v_mfma_f32_16x16x32_bf16 v[2:5], v[158:161], v[206:209], v[2:5]
	s_barrier
	s_add_i32 s71, s71, 2
	s_add_u32 s69, s69, 0x100
	s_addc_u32 s70, s70, 0
	s_cmpk_gt_u32 s71, 0xdd
	s_mov_b64 s[18:19], s[36:37]
